# combination on v74: LN sample-row gamma/beta hoist + all scan helper conversion blocks read LDS in one batch + prep state-copy loads batched
# speedup vs baseline: 1.0092x; 1.0007x over previous
.LBB0_1258:
	v_readlane_b32 s0, v251, 12
	v_readlane_b32 s1, v251, 13
	s_andn2_b64 vcc, exec, s[0:1]
	s_cbranch_vccnz .LBB0_1786
	s_and_b32 s0, s13, 7
	s_cmp_eq_u32 s0, 2
	s_cselect_b64 s[0:1], -1, 0
	s_cmpk_lt_u32 s13, 0x70
	s_cselect_b64 s[2:3], -1, 0
	s_and_b64 s[0:1], s[0:1], s[2:3]
	s_andn2_b64 vcc, exec, s[0:1]
	s_cbranch_vccnz .LBB0_1786
	s_and_b32 s0, s12, 0x3c00
	s_add_i32 s46, s0, s51
	s_mov_b32 s26, 9
	s_mov_b32 s90, 25
	s_mov_b32 s2, 28
	s_mov_b32 s96, 29
	s_mov_b32 s24, 30
	s_mov_b32 s30, 31
	s_mov_b32 s0, 34
	s_mov_b32 s4, 35
	s_mov_b32 s18, 36
	s_mov_b32 s34, 12
	s_mov_b32 s54, 14
	s_mov_b32 s38, 15
	s_cmpk_gt_i32 s46, 0x37df
	s_cbranch_scc1 .LBB0_1785
	s_cmpk_gt_i32 s46, 0xe9f
	s_mov_b64 s[44:45], -1
	s_cbranch_scc0 .LBB0_1735
	v_writelane_b32 v250, s0, 28
	s_cmpk_gt_u32 s46, 0x199f
	s_nop 0
	v_writelane_b32 v250, s1, 29
	s_cbranch_scc0 .LBB0_1684
	v_writelane_b32 v250, s4, 42
	s_cmpk_gt_u32 s46, 0x249f
	s_nop 0
	v_writelane_b32 v250, s5, 43
	s_cbranch_scc0 .LBB0_1633
	v_writelane_b32 v250, s18, 44
	s_cmpk_gt_u32 s46, 0x2f9f
	s_nop 0
	v_writelane_b32 v250, s19, 45
	s_cbranch_scc0 .LBB0_1582
	s_cmpk_gt_u32 s46, 0x339f
	s_cbranch_scc0 .LBB0_1531
	s_cmpk_gt_u32 s46, 0x349f
	s_cbranch_scc0 .LBB0_1480
	s_cmpk_gt_u32 s46, 0x359f
	s_cbranch_scc0 .LBB0_1429
	s_cmpk_gt_u32 s46, 0x369f
	s_cbranch_scc0 .LBB0_1378
	s_cmpk_gt_u32 s46, 0x379f
	s_cbranch_scc0 .LBB0_1327
	s_cmpk_gt_u32 s46, 0x37af
	s_cbranch_scc0 .LBB0_1308
	s_cmpk_gt_u32 s46, 0x37bf
	s_cbranch_scc0 .LBB0_1289
	s_ashr_i32 s39, s38, 31
	s_lshl_b64 s[0:1], s[38:39], 3
	v_readlane_b32 s4, v253, 31
	v_readlane_b32 s5, v253, 32
	s_add_u32 s0, s4, s0
	s_addc_u32 s1, s5, s1
	s_add_i32 s3, s46, 0xffffc840
	s_load_dwordx2 s[0:1], s[0:1], 0x0
	s_cmp_gt_u32 s3, 15
	s_cselect_b32 s4, -16, 0
	s_cselect_b32 s18, 64, 0
	s_add_i32 s4, s4, s3
	s_mov_b32 s25, s46
	s_lshl_b32 s46, s4, 6
	v_ashrrev_i32_e32 v116, 4, v115
	s_lshl_b64 s[4:5], s[46:47], 2
	v_add_u32_e32 v42, s18, v116
	s_waitcnt lgkmcnt(0)
	s_add_u32 s0, s0, s4
	v_lshlrev_b32_e32 v0, 4, v115
	s_addc_u32 s1, s1, s5
	v_and_b32_e32 v0, 0xf0, v0
	v_ashrrev_i32_e32 v43, 31, v42
	v_lshl_add_u64 v[44:45], s[0:1], 0, v[0:1]
	v_lshlrev_b64 v[42:43], 12, v[42:43]
	v_lshl_add_u64 v[102:103], v[44:45], 0, v[42:43]
	s_mov_b32 s0, 0x80000
	v_add_co_u32_e32 v42, vcc, s0, v102
	s_mov_b32 s0, 0x84000
	s_nop 0
	v_addc_co_u32_e32 v43, vcc, 0, v103, vcc
	v_add_co_u32_e32 v46, vcc, s0, v102
	s_mov_b32 s0, 0x88000
	s_nop 0
	v_addc_co_u32_e32 v47, vcc, 0, v103, vcc
	global_load_dwordx4 v[42:45], v[42:43], off
	s_nop 0
	global_load_dwordx4 v[46:49], v[46:47], off
	v_add_co_u32_e32 v50, vcc, s0, v102
	s_mov_b32 s0, 0x8c000
	s_nop 0
	v_addc_co_u32_e32 v51, vcc, 0, v103, vcc
	v_add_co_u32_e32 v54, vcc, s0, v102
	s_mov_b32 s0, 0x90000
	s_nop 0
	v_addc_co_u32_e32 v55, vcc, 0, v103, vcc
	global_load_dwordx4 v[50:53], v[50:51], off
	s_nop 0
	global_load_dwordx4 v[54:57], v[54:55], off
	v_add_co_u32_e32 v58, vcc, s0, v102
	s_mov_b32 s0, 0x94000
	s_nop 0
	v_addc_co_u32_e32 v59, vcc, 0, v103, vcc
	v_add_co_u32_e32 v62, vcc, s0, v102
	s_mov_b32 s0, 0x98000
	s_nop 0
	v_addc_co_u32_e32 v63, vcc, 0, v103, vcc
	global_load_dwordx4 v[58:61], v[58:59], off
	s_nop 0
	global_load_dwordx4 v[62:65], v[62:63], off
	v_add_co_u32_e32 v66, vcc, s0, v102
	s_mov_b32 s0, 0x9c000
	s_nop 0
	v_addc_co_u32_e32 v67, vcc, 0, v103, vcc
	v_add_co_u32_e32 v70, vcc, s0, v102
	s_mov_b32 s0, 0xa0000
	s_nop 0
	v_addc_co_u32_e32 v71, vcc, 0, v103, vcc
	global_load_dwordx4 v[66:69], v[66:67], off
	s_nop 0
	global_load_dwordx4 v[70:73], v[70:71], off
	v_add_co_u32_e32 v74, vcc, s0, v102
	s_mov_b32 s0, 0xa4000
	s_nop 0
	v_addc_co_u32_e32 v75, vcc, 0, v103, vcc
	v_add_co_u32_e32 v78, vcc, s0, v102
	s_mov_b32 s0, 0xa8000
	s_nop 0
	v_addc_co_u32_e32 v79, vcc, 0, v103, vcc
	global_load_dwordx4 v[74:77], v[74:75], off
	s_nop 0
	global_load_dwordx4 v[78:81], v[78:79], off
	v_add_co_u32_e32 v82, vcc, s0, v102
	s_mov_b32 s0, 0xac000
	s_nop 0
	v_addc_co_u32_e32 v83, vcc, 0, v103, vcc
	v_add_co_u32_e32 v86, vcc, s0, v102
	s_mov_b32 s0, 0xb0000
	s_nop 0
	v_addc_co_u32_e32 v87, vcc, 0, v103, vcc
	global_load_dwordx4 v[82:85], v[82:83], off
	s_nop 0
	global_load_dwordx4 v[86:89], v[86:87], off
	v_add_co_u32_e32 v90, vcc, s0, v102
	s_mov_b32 s0, 0xb4000
	s_nop 0
	v_addc_co_u32_e32 v91, vcc, 0, v103, vcc
	global_load_dwordx4 v[90:93], v[90:91], off
	v_add_co_u32_e32 v94, vcc, s0, v102
	s_mov_b32 s0, 0xb8000
	s_nop 0
	v_addc_co_u32_e32 v95, vcc, 0, v103, vcc
	global_load_dwordx4 v[94:97], v[94:95], off
	v_add_co_u32_e32 v98, vcc, s0, v102
	s_mov_b32 s0, 0xbc000
	s_nop 0
	v_addc_co_u32_e32 v99, vcc, 0, v103, vcc
	global_load_dwordx4 v[98:101], v[98:99], off
	v_add_co_u32_e32 v102, vcc, s0, v102
	s_movk_i32 s0, 0x104
	s_nop 0
	v_addc_co_u32_e32 v103, vcc, 0, v103, vcc
	global_load_dwordx4 v[102:105], v[102:103], off
	v_mul_lo_u32 v116, v116, s0
	v_readlane_b32 s1, v251, 59
	s_nop 1
	v_add3_u32 v0, s1, v0, v116
	v_add_u32_e32 v116, 0x2e00, v0
	s_waitcnt vmcnt(15)
	ds_write2_b32 v116, v42, v43 offset1:1
	v_add_u32_e32 v42, 0x2e08, v0
	ds_write2_b32 v42, v44, v45 offset1:1
	v_add_u32_e32 v42, 0x3210, v0
	s_waitcnt vmcnt(14)
	ds_write2_b32 v42, v46, v47 offset1:1
	v_add_u32_e32 v42, 0x3218, v0
	ds_write2_b32 v42, v48, v49 offset1:1
	v_add_u32_e32 v42, 0x3620, v0
	s_waitcnt vmcnt(13)
	ds_write2_b32 v42, v50, v51 offset1:1
	v_add_u32_e32 v42, 0x3628, v0
	ds_write2_b32 v42, v52, v53 offset1:1
	v_add_u32_e32 v42, 0x3a30, v0
	s_waitcnt vmcnt(12)
	ds_write2_b32 v42, v54, v55 offset1:1
	v_add_u32_e32 v42, 0x3a38, v0
	ds_write2_b32 v42, v56, v57 offset1:1
	v_add_u32_e32 v42, 0x3e40, v0
	s_waitcnt vmcnt(11)
	ds_write2_b32 v42, v58, v59 offset1:1
	v_add_u32_e32 v42, 0x3e48, v0
	ds_write2_b32 v42, v60, v61 offset1:1
	v_add_u32_e32 v42, 0x4250, v0
	s_waitcnt vmcnt(10)
	ds_write2_b32 v42, v62, v63 offset1:1
	v_add_u32_e32 v42, 0x4258, v0
	ds_write2_b32 v42, v64, v65 offset1:1
	v_add_u32_e32 v42, 0x4660, v0
	v_ashrrev_i32_e32 v45, 3, v115
	v_add_u32_e32 v44, s46, v45
	s_waitcnt vmcnt(9)
	ds_write2_b32 v42, v66, v67 offset1:1
	v_add_u32_e32 v42, 0x4668, v0
	ds_write2_b32 v42, v68, v69 offset1:1
	v_add_u32_e32 v42, 0x4a70, v0
	s_waitcnt vmcnt(8)
	ds_write2_b32 v42, v70, v71 offset1:1
	v_add_u32_e32 v42, 0x4a78, v0
	ds_write2_b32 v42, v72, v73 offset1:1
	v_add_u32_e32 v42, 0x4e80, v0
	s_waitcnt vmcnt(7)
	ds_write2_b32 v42, v74, v75 offset1:1
	v_add_u32_e32 v42, 0x4e88, v0
	ds_write2_b32 v42, v76, v77 offset1:1
	v_add_u32_e32 v42, 0x5290, v0
	s_waitcnt vmcnt(6)
	ds_write2_b32 v42, v78, v79 offset1:1
	v_add_u32_e32 v42, 0x5298, v0
	ds_write2_b32 v42, v80, v81 offset1:1
	v_add_u32_e32 v42, 0x56a0, v0
	s_waitcnt vmcnt(5)
	ds_write2_b32 v42, v82, v83 offset1:1
	v_add_u32_e32 v42, 0x56a8, v0
	ds_write2_b32 v42, v84, v85 offset1:1
	v_add_u32_e32 v42, 0x5ab0, v0
	s_waitcnt vmcnt(4)
	ds_write2_b32 v42, v86, v87 offset1:1
	v_add_u32_e32 v42, 0x5ab8, v0
	ds_write2_b32 v42, v88, v89 offset1:1
	v_add_u32_e32 v42, 0x5ec0, v0
	s_waitcnt vmcnt(3)
	ds_write2_b32 v42, v90, v91 offset1:1
	v_add_u32_e32 v42, 0x5ec8, v0
	ds_write2_b32 v42, v92, v93 offset1:1
	v_add_u32_e32 v42, 0x62d0, v0
	s_waitcnt vmcnt(2)
	ds_write2_b32 v42, v94, v95 offset1:1
	v_add_u32_e32 v42, 0x62d8, v0
	ds_write2_b32 v42, v96, v97 offset1:1
	v_add_u32_e32 v42, 0x66e0, v0
	s_waitcnt vmcnt(1)
	ds_write2_b32 v42, v98, v99 offset1:1
	v_add_u32_e32 v42, 0x66e8, v0
	ds_write2_b32 v42, v100, v101 offset1:1
	v_add_u32_e32 v42, 0x6af0, v0
	v_add_u32_e32 v0, 0x6af8, v0
	s_waitcnt vmcnt(0)
	ds_write2_b32 v0, v104, v105 offset1:1
	v_lshlrev_b32_e32 v0, 3, v115
	ds_write2_b32 v42, v102, v103 offset1:1
	v_and_b32_e32 v0, 56, v0
	v_mov_b32_e32 v42, s1
	v_mad_u32_u24 v46, v0, s0, v42
	s_lshl_b32 s0, s18, 1
	v_readlane_b32 s1, v250, 34
	s_add_u32 s0, s1, s0
	v_readlane_b32 s1, v250, 18
	s_waitcnt lgkmcnt(0)
	s_addc_u32 s1, s1, 0
	v_lshlrev_b32_e32 v0, 1, v0
	v_lshl_add_u64 v[42:43], s[0:1], 0, v[0:1]
	s_movk_i32 s0, 0x400
	v_lshl_add_u32 v0, v45, 2, v46
	v_cmp_gt_i32_e32 vcc, s0, v44
	v_add_u32_e32 v49, 0x2c00, v0
	v_add_u32_e32 v48, 0x3000, v0
	v_add_u32_e32 v0, 0x3400, v0
	s_and_saveexec_b64 s[38:39], vcc
	s_cbranch_execz .LBB0_1274
	ds_read2_b32 v[232:233], v49 offset0:128 offset1:193
	ds_read2_b32 v[234:235], v48 offset0:2 offset1:67
	ds_read2_b32 v[236:237], v0 offset0:6 offset1:71
	ds_read2_b32 v[238:239], v48 offset0:132 offset1:197
	s_waitcnt lgkmcnt(0)
	v_bfe_u32 v240, v233, 16, 1
	v_add3_u32 v240, v233, v240, s60
	v_bfe_u32 v241, v232, 16, 1
	v_add3_u32 v241, v232, v241, s60
	v_lshrrev_b32_e32 v241, 16, v241
	v_and_or_b32 v50, v240, s33, v241
	v_bfe_u32 v240, v235, 16, 1
	v_add3_u32 v240, v235, v240, s60
	v_bfe_u32 v241, v234, 16, 1
	v_add3_u32 v241, v234, v241, s60
	v_lshrrev_b32_e32 v241, 16, v241
	v_and_or_b32 v51, v240, s33, v241
	v_bfe_u32 v240, v239, 16, 1
	v_add3_u32 v240, v239, v240, s60
	v_bfe_u32 v241, v238, 16, 1
	v_add3_u32 v241, v238, v241, s60
	v_lshrrev_b32_e32 v241, 16, v241
	v_and_or_b32 v52, v240, s33, v241
	v_bfe_u32 v240, v237, 16, 1
	v_add3_u32 v240, v237, v240, s60
	v_bfe_u32 v241, v236, 16, 1
	v_add3_u32 v241, v236, v241, s60
	v_lshrrev_b32_e32 v241, 16, v241
	v_and_or_b32 v53, v240, s33, v241
	v_ashrrev_i32_e32 v45, 31, v44
	v_lshlrev_b64 v[46:47], 8, v[44:45]
	v_lshl_add_u64 v[46:47], v[42:43], 0, v[46:47]
	global_store_dwordx4 v[46:47], v[50:53], off
.LBB0_1274:
	s_or_b64 exec, exec, s[38:39]
	v_add_u32_e32 v46, 8, v44
	v_cmp_gt_i32_e32 vcc, s0, v46
	s_and_saveexec_b64 s[38:39], vcc
	s_cbranch_execz .LBB0_1276
	ds_read2_b32 v[232:233], v49 offset0:136 offset1:201
	ds_read2_b32 v[234:235], v48 offset0:10 offset1:75
	ds_read2_b32 v[236:237], v0 offset0:14 offset1:79
	ds_read2_b32 v[238:239], v48 offset0:140 offset1:205
	s_waitcnt lgkmcnt(0)
	v_bfe_u32 v240, v233, 16, 1
	v_add3_u32 v240, v233, v240, s60
	v_bfe_u32 v241, v232, 16, 1
	v_add3_u32 v241, v232, v241, s60
	v_lshrrev_b32_e32 v241, 16, v241
	v_and_or_b32 v50, v240, s33, v241
	v_bfe_u32 v240, v235, 16, 1
	v_add3_u32 v240, v235, v240, s60
	v_bfe_u32 v241, v234, 16, 1
	v_add3_u32 v241, v234, v241, s60
	v_lshrrev_b32_e32 v241, 16, v241
	v_and_or_b32 v51, v240, s33, v241
	v_bfe_u32 v240, v239, 16, 1
	v_add3_u32 v240, v239, v240, s60
	v_bfe_u32 v241, v238, 16, 1
	v_add3_u32 v241, v238, v241, s60
	v_lshrrev_b32_e32 v241, 16, v241
	v_and_or_b32 v52, v240, s33, v241
	v_bfe_u32 v240, v237, 16, 1
	v_add3_u32 v240, v237, v240, s60
	v_bfe_u32 v241, v236, 16, 1
	v_add3_u32 v241, v236, v241, s60
	v_lshrrev_b32_e32 v241, 16, v241
	v_and_or_b32 v53, v240, s33, v241
	v_ashrrev_i32_e32 v47, 31, v46
	v_lshlrev_b64 v[46:47], 8, v[46:47]
	v_lshl_add_u64 v[46:47], v[42:43], 0, v[46:47]
	global_store_dwordx4 v[46:47], v[50:53], off
.LBB0_1276:
	s_or_b64 exec, exec, s[38:39]
	v_add_u32_e32 v46, 16, v44
	v_cmp_gt_i32_e32 vcc, s0, v46
	s_and_saveexec_b64 s[38:39], vcc
	s_mov_b32 s46, s25
	s_cbranch_execz .LBB0_1278
	ds_read2_b32 v[232:233], v49 offset0:144 offset1:209
	ds_read2_b32 v[234:235], v48 offset0:18 offset1:83
	ds_read2_b32 v[236:237], v0 offset0:22 offset1:87
	ds_read2_b32 v[238:239], v48 offset0:148 offset1:213
	s_waitcnt lgkmcnt(0)
	v_bfe_u32 v240, v233, 16, 1
	v_add3_u32 v240, v233, v240, s60
	v_bfe_u32 v241, v232, 16, 1
	v_add3_u32 v241, v232, v241, s60
	v_lshrrev_b32_e32 v241, 16, v241
	v_and_or_b32 v50, v240, s33, v241
	v_bfe_u32 v240, v235, 16, 1
	v_add3_u32 v240, v235, v240, s60
	v_bfe_u32 v241, v234, 16, 1
	v_add3_u32 v241, v234, v241, s60
	v_lshrrev_b32_e32 v241, 16, v241
	v_and_or_b32 v51, v240, s33, v241
	v_bfe_u32 v240, v239, 16, 1
	v_add3_u32 v240, v239, v240, s60
	v_bfe_u32 v241, v238, 16, 1
	v_add3_u32 v241, v238, v241, s60
	v_lshrrev_b32_e32 v241, 16, v241
	v_and_or_b32 v52, v240, s33, v241
	v_bfe_u32 v240, v237, 16, 1
	v_add3_u32 v240, v237, v240, s60
	v_bfe_u32 v241, v236, 16, 1
	v_add3_u32 v241, v236, v241, s60
	v_lshrrev_b32_e32 v241, 16, v241
	v_and_or_b32 v53, v240, s33, v241
	v_ashrrev_i32_e32 v47, 31, v46
	v_lshlrev_b64 v[46:47], 8, v[46:47]
	v_lshl_add_u64 v[46:47], v[42:43], 0, v[46:47]
	global_store_dwordx4 v[46:47], v[50:53], off
.LBB0_1278:
	s_or_b64 exec, exec, s[38:39]
	v_add_u32_e32 v46, 24, v44
	v_cmp_gt_i32_e32 vcc, s0, v46
	s_and_saveexec_b64 s[38:39], vcc
	s_cbranch_execz .LBB0_1280
	ds_read2_b32 v[232:233], v49 offset0:152 offset1:217
	ds_read2_b32 v[234:235], v48 offset0:26 offset1:91
	ds_read2_b32 v[236:237], v0 offset0:30 offset1:95
	ds_read2_b32 v[238:239], v48 offset0:156 offset1:221
	s_waitcnt lgkmcnt(0)
	v_bfe_u32 v240, v233, 16, 1
	v_add3_u32 v240, v233, v240, s60
	v_bfe_u32 v241, v232, 16, 1
	v_add3_u32 v241, v232, v241, s60
	v_lshrrev_b32_e32 v241, 16, v241
	v_and_or_b32 v50, v240, s33, v241
	v_bfe_u32 v240, v235, 16, 1
	v_add3_u32 v240, v235, v240, s60
	v_bfe_u32 v241, v234, 16, 1
	v_add3_u32 v241, v234, v241, s60
	v_lshrrev_b32_e32 v241, 16, v241
	v_and_or_b32 v51, v240, s33, v241
	v_bfe_u32 v240, v239, 16, 1
	v_add3_u32 v240, v239, v240, s60
	v_bfe_u32 v241, v238, 16, 1
	v_add3_u32 v241, v238, v241, s60
	v_lshrrev_b32_e32 v241, 16, v241
	v_and_or_b32 v52, v240, s33, v241
	v_bfe_u32 v240, v237, 16, 1
	v_add3_u32 v240, v237, v240, s60
	v_bfe_u32 v241, v236, 16, 1
	v_add3_u32 v241, v236, v241, s60
	v_lshrrev_b32_e32 v241, 16, v241
	v_and_or_b32 v53, v240, s33, v241
	v_ashrrev_i32_e32 v47, 31, v46
	v_lshlrev_b64 v[46:47], 8, v[46:47]
	v_lshl_add_u64 v[46:47], v[42:43], 0, v[46:47]
	global_store_dwordx4 v[46:47], v[50:53], off
.LBB0_1280:
	s_or_b64 exec, exec, s[38:39]
	v_add_u32_e32 v46, 32, v44
	v_cmp_gt_i32_e32 vcc, s0, v46
	s_and_saveexec_b64 s[38:39], vcc
	s_cbranch_execz .LBB0_1282
	ds_read2_b32 v[232:233], v49 offset0:160 offset1:225
	ds_read2_b32 v[234:235], v48 offset0:34 offset1:99
	ds_read2_b32 v[236:237], v0 offset0:38 offset1:103
	ds_read2_b32 v[238:239], v48 offset0:164 offset1:229
	s_waitcnt lgkmcnt(0)
	v_bfe_u32 v240, v233, 16, 1
	v_add3_u32 v240, v233, v240, s60
	v_bfe_u32 v241, v232, 16, 1
	v_add3_u32 v241, v232, v241, s60
	v_lshrrev_b32_e32 v241, 16, v241
	v_and_or_b32 v50, v240, s33, v241
	v_bfe_u32 v240, v235, 16, 1
	v_add3_u32 v240, v235, v240, s60
	v_bfe_u32 v241, v234, 16, 1
	v_add3_u32 v241, v234, v241, s60
	v_lshrrev_b32_e32 v241, 16, v241
	v_and_or_b32 v51, v240, s33, v241
	v_bfe_u32 v240, v239, 16, 1
	v_add3_u32 v240, v239, v240, s60
	v_bfe_u32 v241, v238, 16, 1
	v_add3_u32 v241, v238, v241, s60
	v_lshrrev_b32_e32 v241, 16, v241
	v_and_or_b32 v52, v240, s33, v241
	v_bfe_u32 v240, v237, 16, 1
	v_add3_u32 v240, v237, v240, s60
	v_bfe_u32 v241, v236, 16, 1
	v_add3_u32 v241, v236, v241, s60
	v_lshrrev_b32_e32 v241, 16, v241
	v_and_or_b32 v53, v240, s33, v241
	v_ashrrev_i32_e32 v47, 31, v46
	v_lshlrev_b64 v[46:47], 8, v[46:47]
	v_lshl_add_u64 v[46:47], v[42:43], 0, v[46:47]
	global_store_dwordx4 v[46:47], v[50:53], off
.LBB0_1282:
	s_or_b64 exec, exec, s[38:39]
	v_add_u32_e32 v46, 40, v44
	v_cmp_gt_i32_e32 vcc, s0, v46
	s_and_saveexec_b64 s[38:39], vcc
	s_cbranch_execz .LBB0_1284
	ds_read2_b32 v[232:233], v49 offset0:168 offset1:233
	ds_read2_b32 v[234:235], v48 offset0:42 offset1:107
	ds_read2_b32 v[236:237], v0 offset0:46 offset1:111
	ds_read2_b32 v[238:239], v48 offset0:172 offset1:237
	s_waitcnt lgkmcnt(0)
	v_bfe_u32 v240, v233, 16, 1
	v_add3_u32 v240, v233, v240, s60
	v_bfe_u32 v241, v232, 16, 1
	v_add3_u32 v241, v232, v241, s60
	v_lshrrev_b32_e32 v241, 16, v241
	v_and_or_b32 v50, v240, s33, v241
	v_bfe_u32 v240, v235, 16, 1
	v_add3_u32 v240, v235, v240, s60
	v_bfe_u32 v241, v234, 16, 1
	v_add3_u32 v241, v234, v241, s60
	v_lshrrev_b32_e32 v241, 16, v241
	v_and_or_b32 v51, v240, s33, v241
	v_bfe_u32 v240, v239, 16, 1
	v_add3_u32 v240, v239, v240, s60
	v_bfe_u32 v241, v238, 16, 1
	v_add3_u32 v241, v238, v241, s60
	v_lshrrev_b32_e32 v241, 16, v241
	v_and_or_b32 v52, v240, s33, v241
	v_bfe_u32 v240, v237, 16, 1
	v_add3_u32 v240, v237, v240, s60
	v_bfe_u32 v241, v236, 16, 1
	v_add3_u32 v241, v236, v241, s60
	v_lshrrev_b32_e32 v241, 16, v241
	v_and_or_b32 v53, v240, s33, v241
	v_ashrrev_i32_e32 v47, 31, v46
	v_lshlrev_b64 v[46:47], 8, v[46:47]
	v_lshl_add_u64 v[46:47], v[42:43], 0, v[46:47]
	global_store_dwordx4 v[46:47], v[50:53], off
.LBB0_1284:
	s_or_b64 exec, exec, s[38:39]
	v_add_u32_e32 v46, 48, v44
	v_cmp_gt_i32_e32 vcc, s0, v46
	s_and_saveexec_b64 s[38:39], vcc
	s_cbranch_execz .LBB0_1286
	ds_read2_b32 v[232:233], v49 offset0:176 offset1:241
	ds_read2_b32 v[234:235], v48 offset0:50 offset1:115
	ds_read2_b32 v[236:237], v0 offset0:54 offset1:119
	ds_read2_b32 v[238:239], v48 offset0:180 offset1:245
	s_waitcnt lgkmcnt(0)
	v_bfe_u32 v240, v233, 16, 1
	v_add3_u32 v240, v233, v240, s60
	v_bfe_u32 v241, v232, 16, 1
	v_add3_u32 v241, v232, v241, s60
	v_lshrrev_b32_e32 v241, 16, v241
	v_and_or_b32 v50, v240, s33, v241
	v_bfe_u32 v240, v235, 16, 1
	v_add3_u32 v240, v235, v240, s60
	v_bfe_u32 v241, v234, 16, 1
	v_add3_u32 v241, v234, v241, s60
	v_lshrrev_b32_e32 v241, 16, v241
	v_and_or_b32 v51, v240, s33, v241
	v_bfe_u32 v240, v239, 16, 1
	v_add3_u32 v240, v239, v240, s60
	v_bfe_u32 v241, v238, 16, 1
	v_add3_u32 v241, v238, v241, s60
	v_lshrrev_b32_e32 v241, 16, v241
	v_and_or_b32 v52, v240, s33, v241
	v_bfe_u32 v240, v237, 16, 1
	v_add3_u32 v240, v237, v240, s60
	v_bfe_u32 v241, v236, 16, 1
	v_add3_u32 v241, v236, v241, s60
	v_lshrrev_b32_e32 v241, 16, v241
	v_and_or_b32 v53, v240, s33, v241
	v_ashrrev_i32_e32 v47, 31, v46
	v_lshlrev_b64 v[46:47], 8, v[46:47]
	v_lshl_add_u64 v[46:47], v[42:43], 0, v[46:47]
	global_store_dwordx4 v[46:47], v[50:53], off
.LBB0_1286:
	s_or_b64 exec, exec, s[38:39]
	v_add_u32_e32 v44, 56, v44
	v_cmp_gt_i32_e32 vcc, s0, v44
	s_and_saveexec_b64 s[38:39], vcc
	s_cbranch_execz .LBB0_1288
	ds_read2_b32 v[232:233], v49 offset0:184 offset1:249
	ds_read2_b32 v[234:235], v48 offset0:58 offset1:123
	ds_read2_b32 v[236:237], v48 offset0:188 offset1:253
	ds_read2_b32 v[238:239], v0 offset0:62 offset1:127
	s_waitcnt lgkmcnt(0)
	v_bfe_u32 v240, v233, 16, 1
	v_add3_u32 v240, v233, v240, s60
	v_bfe_u32 v241, v232, 16, 1
	v_add3_u32 v241, v232, v241, s60
	v_lshrrev_b32_e32 v241, 16, v241
	v_and_or_b32 v46, v240, s33, v241
	v_bfe_u32 v240, v235, 16, 1
	v_add3_u32 v240, v235, v240, s60
	v_bfe_u32 v241, v234, 16, 1
	v_add3_u32 v241, v234, v241, s60
	v_lshrrev_b32_e32 v241, 16, v241
	v_and_or_b32 v47, v240, s33, v241
	v_bfe_u32 v240, v237, 16, 1
	v_add3_u32 v240, v237, v240, s60
	v_bfe_u32 v241, v236, 16, 1
	v_add3_u32 v241, v236, v241, s60
	v_lshrrev_b32_e32 v241, 16, v241
	v_and_or_b32 v48, v240, s33, v241
	v_bfe_u32 v240, v239, 16, 1
	v_add3_u32 v240, v239, v240, s60
	v_bfe_u32 v241, v238, 16, 1
	v_add3_u32 v241, v238, v241, s60
	v_lshrrev_b32_e32 v241, 16, v241
	v_and_or_b32 v49, v240, s33, v241
	v_ashrrev_i32_e32 v45, 31, v44
	v_lshlrev_b64 v[44:45], 8, v[44:45]
	v_lshl_add_u64 v[42:43], v[42:43], 0, v[44:45]
	global_store_dwordx4 v[42:43], v[46:49], off

.LBB0_1289:
	s_and_b64 vcc, exec, s[44:45]
	s_cbranch_vccz .LBB0_1307
	s_mov_b32 s18, s55
	s_ashr_i32 s55, s54, 31
	s_lshl_b64 s[0:1], s[54:55], 3
	v_readlane_b32 s4, v253, 31
	v_readlane_b32 s5, v253, 32
	s_add_u32 s0, s4, s0
	s_addc_u32 s1, s5, s1
	s_load_dwordx2 s[0:1], s[0:1], 0x0
	s_lshl_b32 s3, s46, 6
	s_mov_b32 s25, s46
	s_add_i32 s46, s3, 0xfff21400
	s_lshl_b64 s[4:5], s[46:47], 2
	v_ashrrev_i32_e32 v116, 4, v115
	s_waitcnt lgkmcnt(0)
	s_add_u32 s0, s0, s4
	v_lshlrev_b32_e32 v0, 4, v115
	s_addc_u32 s1, s1, s5
	v_and_b32_e32 v0, 0xf0, v0
	v_ashrrev_i32_e32 v117, 31, v116
	v_lshl_add_u64 v[42:43], s[0:1], 0, v[0:1]
	v_lshlrev_b64 v[44:45], 12, v[116:117]
	v_lshl_add_u64 v[102:103], v[42:43], 0, v[44:45]
	s_mov_b32 s0, 0x40000
	v_add_co_u32_e32 v42, vcc, s0, v102
	s_mov_b32 s0, 0x44000
	s_nop 0
	v_addc_co_u32_e32 v43, vcc, 0, v103, vcc
	v_add_co_u32_e32 v46, vcc, s0, v102
	s_mov_b32 s0, 0x48000
	s_nop 0
	v_addc_co_u32_e32 v47, vcc, 0, v103, vcc
	global_load_dwordx4 v[42:45], v[42:43], off
	s_nop 0
	global_load_dwordx4 v[46:49], v[46:47], off
	v_add_co_u32_e32 v50, vcc, s0, v102
	s_mov_b32 s0, 0x4c000
	s_nop 0
	v_addc_co_u32_e32 v51, vcc, 0, v103, vcc
	v_add_co_u32_e32 v54, vcc, s0, v102
	s_mov_b32 s0, 0x50000
	s_nop 0
	v_addc_co_u32_e32 v55, vcc, 0, v103, vcc
	global_load_dwordx4 v[50:53], v[50:51], off
	s_nop 0
	global_load_dwordx4 v[54:57], v[54:55], off
	v_add_co_u32_e32 v58, vcc, s0, v102
	s_mov_b32 s0, 0x54000
	s_nop 0
	v_addc_co_u32_e32 v59, vcc, 0, v103, vcc
	v_add_co_u32_e32 v62, vcc, s0, v102
	s_mov_b32 s0, 0x58000
	s_nop 0
	v_addc_co_u32_e32 v63, vcc, 0, v103, vcc
	global_load_dwordx4 v[58:61], v[58:59], off
	s_nop 0
	global_load_dwordx4 v[62:65], v[62:63], off
	v_add_co_u32_e32 v66, vcc, s0, v102
	s_mov_b32 s0, 0x5c000
	s_nop 0
	v_addc_co_u32_e32 v67, vcc, 0, v103, vcc
	v_add_co_u32_e32 v70, vcc, s0, v102
	s_mov_b32 s0, 0x60000
	s_nop 0
	v_addc_co_u32_e32 v71, vcc, 0, v103, vcc
	global_load_dwordx4 v[66:69], v[66:67], off
	s_nop 0
	global_load_dwordx4 v[70:73], v[70:71], off
	v_add_co_u32_e32 v74, vcc, s0, v102
	s_mov_b32 s0, 0x64000
	s_nop 0
	v_addc_co_u32_e32 v75, vcc, 0, v103, vcc
	v_add_co_u32_e32 v78, vcc, s0, v102
	s_mov_b32 s0, 0x68000
	s_nop 0
	v_addc_co_u32_e32 v79, vcc, 0, v103, vcc
	global_load_dwordx4 v[74:77], v[74:75], off
	s_nop 0
	global_load_dwordx4 v[78:81], v[78:79], off
	v_add_co_u32_e32 v82, vcc, s0, v102
	s_mov_b32 s0, 0x6c000
	s_nop 0
	v_addc_co_u32_e32 v83, vcc, 0, v103, vcc
	v_add_co_u32_e32 v86, vcc, s0, v102
	s_mov_b32 s0, 0x70000
	s_nop 0
	v_addc_co_u32_e32 v87, vcc, 0, v103, vcc
	global_load_dwordx4 v[82:85], v[82:83], off
	s_nop 0
	global_load_dwordx4 v[86:89], v[86:87], off
	v_add_co_u32_e32 v90, vcc, s0, v102
	s_mov_b32 s0, 0x74000
	s_nop 0
	v_addc_co_u32_e32 v91, vcc, 0, v103, vcc
	global_load_dwordx4 v[90:93], v[90:91], off
	v_add_co_u32_e32 v94, vcc, s0, v102
	s_mov_b32 s0, 0x78000
	s_nop 0
	v_addc_co_u32_e32 v95, vcc, 0, v103, vcc
	global_load_dwordx4 v[94:97], v[94:95], off
	v_add_co_u32_e32 v98, vcc, s0, v102
	s_mov_b32 s0, 0x7c000
	s_nop 0
	v_addc_co_u32_e32 v99, vcc, 0, v103, vcc
	global_load_dwordx4 v[98:101], v[98:99], off
	v_add_co_u32_e32 v102, vcc, s0, v102
	s_movk_i32 s0, 0x104
	s_nop 0
	v_addc_co_u32_e32 v103, vcc, 0, v103, vcc
	global_load_dwordx4 v[102:105], v[102:103], off
	v_mul_lo_u32 v116, v116, s0
	v_readlane_b32 s1, v251, 59
	s_movk_i32 s3, 0x400
	s_nop 0
	v_add3_u32 v0, s1, v0, v116
	v_add_u32_e32 v116, 0x2e00, v0
	s_waitcnt vmcnt(15)
	ds_write2_b32 v116, v42, v43 offset1:1
	v_add_u32_e32 v42, 0x2e08, v0
	ds_write2_b32 v42, v44, v45 offset1:1
	v_add_u32_e32 v42, 0x3210, v0
	s_waitcnt vmcnt(14)
	ds_write2_b32 v42, v46, v47 offset1:1
	v_add_u32_e32 v42, 0x3218, v0
	ds_write2_b32 v42, v48, v49 offset1:1
	v_add_u32_e32 v42, 0x3620, v0
	s_waitcnt vmcnt(13)
	ds_write2_b32 v42, v50, v51 offset1:1
	v_add_u32_e32 v42, 0x3628, v0
	ds_write2_b32 v42, v52, v53 offset1:1
	v_add_u32_e32 v42, 0x3a30, v0
	s_waitcnt vmcnt(12)
	ds_write2_b32 v42, v54, v55 offset1:1
	v_add_u32_e32 v42, 0x3a38, v0
	ds_write2_b32 v42, v56, v57 offset1:1
	v_add_u32_e32 v42, 0x3e40, v0
	s_waitcnt vmcnt(11)
	ds_write2_b32 v42, v58, v59 offset1:1
	v_add_u32_e32 v42, 0x3e48, v0
	ds_write2_b32 v42, v60, v61 offset1:1
	v_add_u32_e32 v42, 0x4250, v0
	s_waitcnt vmcnt(10)
	ds_write2_b32 v42, v62, v63 offset1:1
	v_add_u32_e32 v42, 0x4258, v0
	ds_write2_b32 v42, v64, v65 offset1:1
	v_add_u32_e32 v42, 0x4660, v0
	v_ashrrev_i32_e32 v45, 3, v115
	v_add_u32_e32 v44, s46, v45
	s_waitcnt vmcnt(9)
	ds_write2_b32 v42, v66, v67 offset1:1
	v_add_u32_e32 v42, 0x4668, v0
	ds_write2_b32 v42, v68, v69 offset1:1
	v_add_u32_e32 v42, 0x4a70, v0
	s_waitcnt vmcnt(8)
	ds_write2_b32 v42, v70, v71 offset1:1
	v_add_u32_e32 v42, 0x4a78, v0
	ds_write2_b32 v42, v72, v73 offset1:1
	v_add_u32_e32 v42, 0x4e80, v0
	v_cmp_gt_i32_e32 vcc, s3, v44
	s_waitcnt vmcnt(7)
	ds_write2_b32 v42, v74, v75 offset1:1
	v_add_u32_e32 v42, 0x4e88, v0
	ds_write2_b32 v42, v76, v77 offset1:1
	v_add_u32_e32 v42, 0x5290, v0
	s_waitcnt vmcnt(6)
	ds_write2_b32 v42, v78, v79 offset1:1
	v_add_u32_e32 v42, 0x5298, v0
	ds_write2_b32 v42, v80, v81 offset1:1
	v_add_u32_e32 v42, 0x56a0, v0
	s_waitcnt vmcnt(5)
	ds_write2_b32 v42, v82, v83 offset1:1
	v_add_u32_e32 v42, 0x56a8, v0
	ds_write2_b32 v42, v84, v85 offset1:1
	v_add_u32_e32 v42, 0x5ab0, v0
	s_waitcnt vmcnt(4)
	ds_write2_b32 v42, v86, v87 offset1:1
	v_add_u32_e32 v42, 0x5ab8, v0
	ds_write2_b32 v42, v88, v89 offset1:1
	v_add_u32_e32 v42, 0x5ec0, v0
	s_waitcnt vmcnt(3)
	ds_write2_b32 v42, v90, v91 offset1:1
	v_add_u32_e32 v42, 0x5ec8, v0
	ds_write2_b32 v42, v92, v93 offset1:1
	v_add_u32_e32 v42, 0x62d0, v0
	s_waitcnt vmcnt(2)
	ds_write2_b32 v42, v94, v95 offset1:1
	v_add_u32_e32 v42, 0x62d8, v0
	ds_write2_b32 v42, v96, v97 offset1:1
	v_add_u32_e32 v42, 0x66e0, v0
	s_waitcnt vmcnt(1)
	ds_write2_b32 v42, v98, v99 offset1:1
	v_add_u32_e32 v42, 0x66e8, v0
	ds_write2_b32 v42, v100, v101 offset1:1
	v_add_u32_e32 v42, 0x6af0, v0
	v_add_u32_e32 v0, 0x6af8, v0
	s_waitcnt vmcnt(0)
	ds_write2_b32 v0, v104, v105 offset1:1
	v_lshlrev_b32_e32 v0, 3, v115
	ds_write2_b32 v42, v102, v103 offset1:1
	v_and_b32_e32 v0, 56, v0
	v_mov_b32_e32 v42, s1
	v_mad_u32_u24 v46, v0, s0, v42
	v_readlane_b32 s0, v250, 40
	s_waitcnt lgkmcnt(0)
	v_lshlrev_b32_e32 v0, 1, v0
	v_readlane_b32 s1, v250, 41
	s_nop 1
	v_lshl_add_u64 v[42:43], s[0:1], 0, v[0:1]
	v_lshl_add_u32 v0, v45, 2, v46
	v_add_u32_e32 v49, 0x2c00, v0
	v_add_u32_e32 v48, 0x3000, v0
	v_add_u32_e32 v0, 0x3400, v0
	s_and_saveexec_b64 s[38:39], vcc
	s_cbranch_execz .LBB0_1292
	ds_read2_b32 v[232:233], v49 offset0:128 offset1:193
	ds_read2_b32 v[234:235], v48 offset0:2 offset1:67
	ds_read2_b32 v[236:237], v0 offset0:6 offset1:71
	ds_read2_b32 v[238:239], v48 offset0:132 offset1:197
	s_waitcnt lgkmcnt(0)
	v_bfe_u32 v240, v233, 16, 1
	v_add3_u32 v240, v233, v240, s60
	v_bfe_u32 v241, v232, 16, 1
	v_add3_u32 v241, v232, v241, s60
	v_lshrrev_b32_e32 v241, 16, v241
	v_and_or_b32 v50, v240, s33, v241
	v_bfe_u32 v240, v235, 16, 1
	v_add3_u32 v240, v235, v240, s60
	v_bfe_u32 v241, v234, 16, 1
	v_add3_u32 v241, v234, v241, s60
	v_lshrrev_b32_e32 v241, 16, v241
	v_and_or_b32 v51, v240, s33, v241
	v_bfe_u32 v240, v239, 16, 1
	v_add3_u32 v240, v239, v240, s60
	v_bfe_u32 v241, v238, 16, 1
	v_add3_u32 v241, v238, v241, s60
	v_lshrrev_b32_e32 v241, 16, v241
	v_and_or_b32 v52, v240, s33, v241
	v_bfe_u32 v240, v237, 16, 1
	v_add3_u32 v240, v237, v240, s60
	v_bfe_u32 v241, v236, 16, 1
	v_add3_u32 v241, v236, v241, s60
	v_lshrrev_b32_e32 v241, 16, v241
	v_and_or_b32 v53, v240, s33, v241
	v_ashrrev_i32_e32 v45, 31, v44
	v_lshlrev_b64 v[46:47], 7, v[44:45]
	v_lshl_add_u64 v[46:47], v[42:43], 0, v[46:47]
	global_store_dwordx4 v[46:47], v[50:53], off
.LBB0_1292:
	s_or_b64 exec, exec, s[38:39]
	v_add_u32_e32 v46, 8, v44
	v_cmp_gt_i32_e32 vcc, s3, v46
	s_and_saveexec_b64 s[38:39], vcc
	s_cbranch_execz .LBB0_1294
	ds_read2_b32 v[232:233], v49 offset0:136 offset1:201
	ds_read2_b32 v[234:235], v48 offset0:10 offset1:75
	ds_read2_b32 v[236:237], v0 offset0:14 offset1:79
	ds_read2_b32 v[238:239], v48 offset0:140 offset1:205
	s_waitcnt lgkmcnt(0)
	v_bfe_u32 v240, v233, 16, 1
	v_add3_u32 v240, v233, v240, s60
	v_bfe_u32 v241, v232, 16, 1
	v_add3_u32 v241, v232, v241, s60
	v_lshrrev_b32_e32 v241, 16, v241
	v_and_or_b32 v50, v240, s33, v241
	v_bfe_u32 v240, v235, 16, 1
	v_add3_u32 v240, v235, v240, s60
	v_bfe_u32 v241, v234, 16, 1
	v_add3_u32 v241, v234, v241, s60
	v_lshrrev_b32_e32 v241, 16, v241
	v_and_or_b32 v51, v240, s33, v241
	v_bfe_u32 v240, v239, 16, 1
	v_add3_u32 v240, v239, v240, s60
	v_bfe_u32 v241, v238, 16, 1
	v_add3_u32 v241, v238, v241, s60
	v_lshrrev_b32_e32 v241, 16, v241
	v_and_or_b32 v52, v240, s33, v241
	v_bfe_u32 v240, v237, 16, 1
	v_add3_u32 v240, v237, v240, s60
	v_bfe_u32 v241, v236, 16, 1
	v_add3_u32 v241, v236, v241, s60
	v_lshrrev_b32_e32 v241, 16, v241
	v_and_or_b32 v53, v240, s33, v241
	v_ashrrev_i32_e32 v47, 31, v46
	v_lshlrev_b64 v[46:47], 7, v[46:47]
	v_lshl_add_u64 v[46:47], v[42:43], 0, v[46:47]
	global_store_dwordx4 v[46:47], v[50:53], off
.LBB0_1294:
	s_or_b64 exec, exec, s[38:39]
	v_add_u32_e32 v46, 16, v44
	v_cmp_gt_i32_e32 vcc, s3, v46
	s_and_saveexec_b64 s[38:39], vcc
	s_mov_b32 s55, s18
	s_mov_b32 s46, s25
	s_cbranch_execz .LBB0_1296
	ds_read2_b32 v[232:233], v49 offset0:144 offset1:209
	ds_read2_b32 v[234:235], v48 offset0:18 offset1:83
	ds_read2_b32 v[236:237], v0 offset0:22 offset1:87
	ds_read2_b32 v[238:239], v48 offset0:148 offset1:213
	s_waitcnt lgkmcnt(0)
	v_bfe_u32 v240, v233, 16, 1
	v_add3_u32 v240, v233, v240, s60
	v_bfe_u32 v241, v232, 16, 1
	v_add3_u32 v241, v232, v241, s60
	v_lshrrev_b32_e32 v241, 16, v241
	v_and_or_b32 v50, v240, s33, v241
	v_bfe_u32 v240, v235, 16, 1
	v_add3_u32 v240, v235, v240, s60
	v_bfe_u32 v241, v234, 16, 1
	v_add3_u32 v241, v234, v241, s60
	v_lshrrev_b32_e32 v241, 16, v241
	v_and_or_b32 v51, v240, s33, v241
	v_bfe_u32 v240, v239, 16, 1
	v_add3_u32 v240, v239, v240, s60
	v_bfe_u32 v241, v238, 16, 1
	v_add3_u32 v241, v238, v241, s60
	v_lshrrev_b32_e32 v241, 16, v241
	v_and_or_b32 v52, v240, s33, v241
	v_bfe_u32 v240, v237, 16, 1
	v_add3_u32 v240, v237, v240, s60
	v_bfe_u32 v241, v236, 16, 1
	v_add3_u32 v241, v236, v241, s60
	v_lshrrev_b32_e32 v241, 16, v241
	v_and_or_b32 v53, v240, s33, v241
	v_ashrrev_i32_e32 v47, 31, v46
	v_lshlrev_b64 v[46:47], 7, v[46:47]
	v_lshl_add_u64 v[46:47], v[42:43], 0, v[46:47]
	global_store_dwordx4 v[46:47], v[50:53], off
.LBB0_1296:
	s_or_b64 exec, exec, s[38:39]
	v_add_u32_e32 v46, 24, v44
	v_cmp_gt_i32_e32 vcc, s3, v46
	s_and_saveexec_b64 s[38:39], vcc
	s_cbranch_execz .LBB0_1298
	ds_read2_b32 v[232:233], v49 offset0:152 offset1:217
	ds_read2_b32 v[234:235], v48 offset0:26 offset1:91
	ds_read2_b32 v[236:237], v0 offset0:30 offset1:95
	ds_read2_b32 v[238:239], v48 offset0:156 offset1:221
	s_waitcnt lgkmcnt(0)
	v_bfe_u32 v240, v233, 16, 1
	v_add3_u32 v240, v233, v240, s60
	v_bfe_u32 v241, v232, 16, 1
	v_add3_u32 v241, v232, v241, s60
	v_lshrrev_b32_e32 v241, 16, v241
	v_and_or_b32 v50, v240, s33, v241
	v_bfe_u32 v240, v235, 16, 1
	v_add3_u32 v240, v235, v240, s60
	v_bfe_u32 v241, v234, 16, 1
	v_add3_u32 v241, v234, v241, s60
	v_lshrrev_b32_e32 v241, 16, v241
	v_and_or_b32 v51, v240, s33, v241
	v_bfe_u32 v240, v239, 16, 1
	v_add3_u32 v240, v239, v240, s60
	v_bfe_u32 v241, v238, 16, 1
	v_add3_u32 v241, v238, v241, s60
	v_lshrrev_b32_e32 v241, 16, v241
	v_and_or_b32 v52, v240, s33, v241
	v_bfe_u32 v240, v237, 16, 1
	v_add3_u32 v240, v237, v240, s60
	v_bfe_u32 v241, v236, 16, 1
	v_add3_u32 v241, v236, v241, s60
	v_lshrrev_b32_e32 v241, 16, v241
	v_and_or_b32 v53, v240, s33, v241
	v_ashrrev_i32_e32 v47, 31, v46
	v_lshlrev_b64 v[46:47], 7, v[46:47]
	v_lshl_add_u64 v[46:47], v[42:43], 0, v[46:47]
	global_store_dwordx4 v[46:47], v[50:53], off
.LBB0_1298:
	s_or_b64 exec, exec, s[38:39]
	v_add_u32_e32 v46, 32, v44
	v_cmp_gt_i32_e32 vcc, s3, v46
	s_and_saveexec_b64 s[38:39], vcc
	s_cbranch_execz .LBB0_1300
	ds_read2_b32 v[232:233], v49 offset0:160 offset1:225
	ds_read2_b32 v[234:235], v48 offset0:34 offset1:99
	ds_read2_b32 v[236:237], v0 offset0:38 offset1:103
	ds_read2_b32 v[238:239], v48 offset0:164 offset1:229
	s_waitcnt lgkmcnt(0)
	v_bfe_u32 v240, v233, 16, 1
	v_add3_u32 v240, v233, v240, s60
	v_bfe_u32 v241, v232, 16, 1
	v_add3_u32 v241, v232, v241, s60
	v_lshrrev_b32_e32 v241, 16, v241
	v_and_or_b32 v50, v240, s33, v241
	v_bfe_u32 v240, v235, 16, 1
	v_add3_u32 v240, v235, v240, s60
	v_bfe_u32 v241, v234, 16, 1
	v_add3_u32 v241, v234, v241, s60
	v_lshrrev_b32_e32 v241, 16, v241
	v_and_or_b32 v51, v240, s33, v241
	v_bfe_u32 v240, v239, 16, 1
	v_add3_u32 v240, v239, v240, s60
	v_bfe_u32 v241, v238, 16, 1
	v_add3_u32 v241, v238, v241, s60
	v_lshrrev_b32_e32 v241, 16, v241
	v_and_or_b32 v52, v240, s33, v241
	v_bfe_u32 v240, v237, 16, 1
	v_add3_u32 v240, v237, v240, s60
	v_bfe_u32 v241, v236, 16, 1
	v_add3_u32 v241, v236, v241, s60
	v_lshrrev_b32_e32 v241, 16, v241
	v_and_or_b32 v53, v240, s33, v241
	v_ashrrev_i32_e32 v47, 31, v46
	v_lshlrev_b64 v[46:47], 7, v[46:47]
	v_lshl_add_u64 v[46:47], v[42:43], 0, v[46:47]
	global_store_dwordx4 v[46:47], v[50:53], off
.LBB0_1300:
	s_or_b64 exec, exec, s[38:39]
	v_add_u32_e32 v46, 40, v44
	v_cmp_gt_i32_e32 vcc, s3, v46
	s_and_saveexec_b64 s[38:39], vcc
	s_cbranch_execz .LBB0_1302
	ds_read2_b32 v[232:233], v49 offset0:168 offset1:233
	ds_read2_b32 v[234:235], v48 offset0:42 offset1:107
	ds_read2_b32 v[236:237], v0 offset0:46 offset1:111
	ds_read2_b32 v[238:239], v48 offset0:172 offset1:237
	s_waitcnt lgkmcnt(0)
	v_bfe_u32 v240, v233, 16, 1
	v_add3_u32 v240, v233, v240, s60
	v_bfe_u32 v241, v232, 16, 1
	v_add3_u32 v241, v232, v241, s60
	v_lshrrev_b32_e32 v241, 16, v241
	v_and_or_b32 v50, v240, s33, v241
	v_bfe_u32 v240, v235, 16, 1
	v_add3_u32 v240, v235, v240, s60
	v_bfe_u32 v241, v234, 16, 1
	v_add3_u32 v241, v234, v241, s60
	v_lshrrev_b32_e32 v241, 16, v241
	v_and_or_b32 v51, v240, s33, v241
	v_bfe_u32 v240, v239, 16, 1
	v_add3_u32 v240, v239, v240, s60
	v_bfe_u32 v241, v238, 16, 1
	v_add3_u32 v241, v238, v241, s60
	v_lshrrev_b32_e32 v241, 16, v241
	v_and_or_b32 v52, v240, s33, v241
	v_bfe_u32 v240, v237, 16, 1
	v_add3_u32 v240, v237, v240, s60
	v_bfe_u32 v241, v236, 16, 1
	v_add3_u32 v241, v236, v241, s60
	v_lshrrev_b32_e32 v241, 16, v241
	v_and_or_b32 v53, v240, s33, v241
	v_ashrrev_i32_e32 v47, 31, v46
	v_lshlrev_b64 v[46:47], 7, v[46:47]
	v_lshl_add_u64 v[46:47], v[42:43], 0, v[46:47]
	global_store_dwordx4 v[46:47], v[50:53], off
.LBB0_1302:
	s_or_b64 exec, exec, s[38:39]
	v_add_u32_e32 v46, 48, v44
	v_cmp_gt_i32_e32 vcc, s3, v46
	s_and_saveexec_b64 s[38:39], vcc
	s_cbranch_execz .LBB0_1304
	ds_read2_b32 v[232:233], v49 offset0:176 offset1:241
	ds_read2_b32 v[234:235], v48 offset0:50 offset1:115
	ds_read2_b32 v[236:237], v0 offset0:54 offset1:119
	ds_read2_b32 v[238:239], v48 offset0:180 offset1:245
	s_waitcnt lgkmcnt(0)
	v_bfe_u32 v240, v233, 16, 1
	v_add3_u32 v240, v233, v240, s60
	v_bfe_u32 v241, v232, 16, 1
	v_add3_u32 v241, v232, v241, s60
	v_lshrrev_b32_e32 v241, 16, v241
	v_and_or_b32 v50, v240, s33, v241
	v_bfe_u32 v240, v235, 16, 1
	v_add3_u32 v240, v235, v240, s60
	v_bfe_u32 v241, v234, 16, 1
	v_add3_u32 v241, v234, v241, s60
	v_lshrrev_b32_e32 v241, 16, v241
	v_and_or_b32 v51, v240, s33, v241
	v_bfe_u32 v240, v239, 16, 1
	v_add3_u32 v240, v239, v240, s60
	v_bfe_u32 v241, v238, 16, 1
	v_add3_u32 v241, v238, v241, s60
	v_lshrrev_b32_e32 v241, 16, v241
	v_and_or_b32 v52, v240, s33, v241
	v_bfe_u32 v240, v237, 16, 1
	v_add3_u32 v240, v237, v240, s60
	v_bfe_u32 v241, v236, 16, 1
	v_add3_u32 v241, v236, v241, s60
	v_lshrrev_b32_e32 v241, 16, v241
	v_and_or_b32 v53, v240, s33, v241
	v_ashrrev_i32_e32 v47, 31, v46
	v_lshlrev_b64 v[46:47], 7, v[46:47]
	v_lshl_add_u64 v[46:47], v[42:43], 0, v[46:47]
	global_store_dwordx4 v[46:47], v[50:53], off
.LBB0_1304:
	s_or_b64 exec, exec, s[38:39]
	v_add_u32_e32 v44, 56, v44
	v_cmp_gt_i32_e32 vcc, s3, v44
	s_and_saveexec_b64 s[38:39], vcc
	s_cbranch_execz .LBB0_1306
	ds_read2_b32 v[232:233], v49 offset0:184 offset1:249
	ds_read2_b32 v[234:235], v48 offset0:58 offset1:123
	ds_read2_b32 v[236:237], v48 offset0:188 offset1:253
	ds_read2_b32 v[238:239], v0 offset0:62 offset1:127
	s_waitcnt lgkmcnt(0)
	v_bfe_u32 v240, v233, 16, 1
	v_add3_u32 v240, v233, v240, s60
	v_bfe_u32 v241, v232, 16, 1
	v_add3_u32 v241, v232, v241, s60
	v_lshrrev_b32_e32 v241, 16, v241
	v_and_or_b32 v46, v240, s33, v241
	v_bfe_u32 v240, v235, 16, 1
	v_add3_u32 v240, v235, v240, s60
	v_bfe_u32 v241, v234, 16, 1
	v_add3_u32 v241, v234, v241, s60
	v_lshrrev_b32_e32 v241, 16, v241
	v_and_or_b32 v47, v240, s33, v241
	v_bfe_u32 v240, v237, 16, 1
	v_add3_u32 v240, v237, v240, s60
	v_bfe_u32 v241, v236, 16, 1
	v_add3_u32 v241, v236, v241, s60
	v_lshrrev_b32_e32 v241, 16, v241
	v_and_or_b32 v48, v240, s33, v241
	v_bfe_u32 v240, v239, 16, 1
	v_add3_u32 v240, v239, v240, s60
	v_bfe_u32 v241, v238, 16, 1
	v_add3_u32 v241, v238, v241, s60
	v_lshrrev_b32_e32 v241, 16, v241
	v_and_or_b32 v49, v240, s33, v241
	v_ashrrev_i32_e32 v45, 31, v44
	v_lshlrev_b64 v[44:45], 7, v[44:45]
	v_lshl_add_u64 v[42:43], v[42:43], 0, v[44:45]
	global_store_dwordx4 v[42:43], v[46:49], off

.LBB0_1308:
	s_andn2_b64 vcc, exec, s[44:45]
	s_cbranch_vccnz .LBB0_1326
	s_ashr_i32 s35, s34, 31
	s_lshl_b64 s[0:1], s[34:35], 3
	v_readlane_b32 s4, v253, 31
	v_readlane_b32 s5, v253, 32
	s_add_u32 s0, s4, s0
	s_addc_u32 s1, s5, s1
	s_load_dwordx2 s[0:1], s[0:1], 0x0
	s_lshl_b32 s3, s46, 6
	s_mov_b32 s18, s46
	s_add_i32 s46, s3, 0xfff21800
	s_lshl_b64 s[4:5], s[46:47], 2
	v_ashrrev_i32_e32 v116, 4, v115
	s_waitcnt lgkmcnt(0)
	s_add_u32 s0, s0, s4
	v_lshlrev_b32_e32 v0, 4, v115
	s_addc_u32 s1, s1, s5
	v_and_b32_e32 v0, 0xf0, v0
	v_ashrrev_i32_e32 v117, 31, v116
	v_lshl_add_u64 v[42:43], s[0:1], 0, v[0:1]
	v_lshlrev_b64 v[44:45], 12, v[116:117]
	v_lshl_add_u64 v[102:103], v[42:43], 0, v[44:45]
	s_mov_b32 s0, 0x40000
	v_add_co_u32_e32 v42, vcc, s0, v102
	s_mov_b32 s0, 0x44000
	s_nop 0
	v_addc_co_u32_e32 v43, vcc, 0, v103, vcc
	v_add_co_u32_e32 v46, vcc, s0, v102
	s_mov_b32 s0, 0x48000
	s_nop 0
	v_addc_co_u32_e32 v47, vcc, 0, v103, vcc
	global_load_dwordx4 v[42:45], v[42:43], off
	s_nop 0
	global_load_dwordx4 v[46:49], v[46:47], off
	v_add_co_u32_e32 v50, vcc, s0, v102
	s_mov_b32 s0, 0x4c000
	s_nop 0
	v_addc_co_u32_e32 v51, vcc, 0, v103, vcc
	v_add_co_u32_e32 v54, vcc, s0, v102
	s_mov_b32 s0, 0x50000
	s_nop 0
	v_addc_co_u32_e32 v55, vcc, 0, v103, vcc
	global_load_dwordx4 v[50:53], v[50:51], off
	s_nop 0
	global_load_dwordx4 v[54:57], v[54:55], off
	v_add_co_u32_e32 v58, vcc, s0, v102
	s_mov_b32 s0, 0x54000
	s_nop 0
	v_addc_co_u32_e32 v59, vcc, 0, v103, vcc
	v_add_co_u32_e32 v62, vcc, s0, v102
	s_mov_b32 s0, 0x58000
	s_nop 0
	v_addc_co_u32_e32 v63, vcc, 0, v103, vcc
	global_load_dwordx4 v[58:61], v[58:59], off
	s_nop 0
	global_load_dwordx4 v[62:65], v[62:63], off
	v_add_co_u32_e32 v66, vcc, s0, v102
	s_mov_b32 s0, 0x5c000
	s_nop 0
	v_addc_co_u32_e32 v67, vcc, 0, v103, vcc
	v_add_co_u32_e32 v70, vcc, s0, v102
	s_mov_b32 s0, 0x60000
	s_nop 0
	v_addc_co_u32_e32 v71, vcc, 0, v103, vcc
	global_load_dwordx4 v[66:69], v[66:67], off
	s_nop 0
	global_load_dwordx4 v[70:73], v[70:71], off
	v_add_co_u32_e32 v74, vcc, s0, v102
	s_mov_b32 s0, 0x64000
	s_nop 0
	v_addc_co_u32_e32 v75, vcc, 0, v103, vcc
	v_add_co_u32_e32 v78, vcc, s0, v102
	s_mov_b32 s0, 0x68000
	s_nop 0
	v_addc_co_u32_e32 v79, vcc, 0, v103, vcc
	global_load_dwordx4 v[74:77], v[74:75], off
	s_nop 0
	global_load_dwordx4 v[78:81], v[78:79], off
	v_add_co_u32_e32 v82, vcc, s0, v102
	s_mov_b32 s0, 0x6c000
	s_nop 0
	v_addc_co_u32_e32 v83, vcc, 0, v103, vcc
	v_add_co_u32_e32 v86, vcc, s0, v102
	s_mov_b32 s0, 0x70000
	s_nop 0
	v_addc_co_u32_e32 v87, vcc, 0, v103, vcc
	global_load_dwordx4 v[82:85], v[82:83], off
	s_nop 0
	global_load_dwordx4 v[86:89], v[86:87], off
	v_add_co_u32_e32 v90, vcc, s0, v102
	s_mov_b32 s0, 0x74000
	s_nop 0
	v_addc_co_u32_e32 v91, vcc, 0, v103, vcc
	global_load_dwordx4 v[90:93], v[90:91], off
	v_add_co_u32_e32 v94, vcc, s0, v102
	s_mov_b32 s0, 0x78000
	s_nop 0
	v_addc_co_u32_e32 v95, vcc, 0, v103, vcc
	global_load_dwordx4 v[94:97], v[94:95], off
	v_add_co_u32_e32 v98, vcc, s0, v102
	s_mov_b32 s0, 0x7c000
	s_nop 0
	v_addc_co_u32_e32 v99, vcc, 0, v103, vcc
	global_load_dwordx4 v[98:101], v[98:99], off
	v_add_co_u32_e32 v102, vcc, s0, v102
	s_movk_i32 s0, 0x104
	s_nop 0
	v_addc_co_u32_e32 v103, vcc, 0, v103, vcc
	global_load_dwordx4 v[102:105], v[102:103], off
	v_mul_lo_u32 v116, v116, s0
	v_readlane_b32 s1, v251, 59
	s_movk_i32 s3, 0x400
	s_nop 0
	v_add3_u32 v0, s1, v0, v116
	v_add_u32_e32 v116, 0x2e00, v0
	s_waitcnt vmcnt(15)
	ds_write2_b32 v116, v42, v43 offset1:1
	v_add_u32_e32 v42, 0x2e08, v0
	ds_write2_b32 v42, v44, v45 offset1:1
	v_add_u32_e32 v42, 0x3210, v0
	s_waitcnt vmcnt(14)
	ds_write2_b32 v42, v46, v47 offset1:1
	v_add_u32_e32 v42, 0x3218, v0
	ds_write2_b32 v42, v48, v49 offset1:1
	v_add_u32_e32 v42, 0x3620, v0
	s_waitcnt vmcnt(13)
	ds_write2_b32 v42, v50, v51 offset1:1
	v_add_u32_e32 v42, 0x3628, v0
	ds_write2_b32 v42, v52, v53 offset1:1
	v_add_u32_e32 v42, 0x3a30, v0
	s_waitcnt vmcnt(12)
	ds_write2_b32 v42, v54, v55 offset1:1
	v_add_u32_e32 v42, 0x3a38, v0
	ds_write2_b32 v42, v56, v57 offset1:1
	v_add_u32_e32 v42, 0x3e40, v0
	s_waitcnt vmcnt(11)
	ds_write2_b32 v42, v58, v59 offset1:1
	v_add_u32_e32 v42, 0x3e48, v0
	ds_write2_b32 v42, v60, v61 offset1:1
	v_add_u32_e32 v42, 0x4250, v0
	s_waitcnt vmcnt(10)
	ds_write2_b32 v42, v62, v63 offset1:1
	v_add_u32_e32 v42, 0x4258, v0
	ds_write2_b32 v42, v64, v65 offset1:1
	v_add_u32_e32 v42, 0x4660, v0
	v_ashrrev_i32_e32 v45, 3, v115
	v_add_u32_e32 v44, s46, v45
	s_waitcnt vmcnt(9)
	ds_write2_b32 v42, v66, v67 offset1:1
	v_add_u32_e32 v42, 0x4668, v0
	ds_write2_b32 v42, v68, v69 offset1:1
	v_add_u32_e32 v42, 0x4a70, v0
	s_waitcnt vmcnt(8)
	ds_write2_b32 v42, v70, v71 offset1:1
	v_add_u32_e32 v42, 0x4a78, v0
	ds_write2_b32 v42, v72, v73 offset1:1
	v_add_u32_e32 v42, 0x4e80, v0
	v_cmp_gt_i32_e32 vcc, s3, v44
	s_waitcnt vmcnt(7)
	ds_write2_b32 v42, v74, v75 offset1:1
	v_add_u32_e32 v42, 0x4e88, v0
	ds_write2_b32 v42, v76, v77 offset1:1
	v_add_u32_e32 v42, 0x5290, v0
	s_waitcnt vmcnt(6)
	ds_write2_b32 v42, v78, v79 offset1:1
	v_add_u32_e32 v42, 0x5298, v0
	ds_write2_b32 v42, v80, v81 offset1:1
	v_add_u32_e32 v42, 0x56a0, v0
	s_waitcnt vmcnt(5)
	ds_write2_b32 v42, v82, v83 offset1:1
	v_add_u32_e32 v42, 0x56a8, v0
	ds_write2_b32 v42, v84, v85 offset1:1
	v_add_u32_e32 v42, 0x5ab0, v0
	s_waitcnt vmcnt(4)
	ds_write2_b32 v42, v86, v87 offset1:1
	v_add_u32_e32 v42, 0x5ab8, v0
	ds_write2_b32 v42, v88, v89 offset1:1
	v_add_u32_e32 v42, 0x5ec0, v0
	s_waitcnt vmcnt(3)
	ds_write2_b32 v42, v90, v91 offset1:1
	v_add_u32_e32 v42, 0x5ec8, v0
	ds_write2_b32 v42, v92, v93 offset1:1
	v_add_u32_e32 v42, 0x62d0, v0
	s_waitcnt vmcnt(2)
	ds_write2_b32 v42, v94, v95 offset1:1
	v_add_u32_e32 v42, 0x62d8, v0
	ds_write2_b32 v42, v96, v97 offset1:1
	v_add_u32_e32 v42, 0x66e0, v0
	s_waitcnt vmcnt(1)
	ds_write2_b32 v42, v98, v99 offset1:1
	v_add_u32_e32 v42, 0x66e8, v0
	ds_write2_b32 v42, v100, v101 offset1:1
	v_add_u32_e32 v42, 0x6af0, v0
	v_add_u32_e32 v0, 0x6af8, v0
	s_waitcnt vmcnt(0)
	ds_write2_b32 v0, v104, v105 offset1:1
	v_lshlrev_b32_e32 v0, 3, v115
	ds_write2_b32 v42, v102, v103 offset1:1
	v_and_b32_e32 v0, 56, v0
	v_mov_b32_e32 v42, s1
	v_mad_u32_u24 v46, v0, s0, v42
	v_readlane_b32 s0, v250, 24
	s_waitcnt lgkmcnt(0)
	v_lshlrev_b32_e32 v0, 1, v0
	v_readlane_b32 s1, v250, 25
	s_nop 1
	v_lshl_add_u64 v[42:43], s[0:1], 0, v[0:1]
	v_lshl_add_u32 v0, v45, 2, v46
	v_add_u32_e32 v49, 0x2c00, v0
	v_add_u32_e32 v48, 0x3000, v0
	v_add_u32_e32 v0, 0x3400, v0
	s_and_saveexec_b64 s[34:35], vcc
	s_cbranch_execz .LBB0_1311
	ds_read2_b32 v[232:233], v49 offset0:128 offset1:193
	ds_read2_b32 v[234:235], v48 offset0:2 offset1:67
	ds_read2_b32 v[236:237], v0 offset0:6 offset1:71
	ds_read2_b32 v[238:239], v48 offset0:132 offset1:197
	s_waitcnt lgkmcnt(0)
	v_bfe_u32 v240, v233, 16, 1
	v_add3_u32 v240, v233, v240, s60
	v_bfe_u32 v241, v232, 16, 1
	v_add3_u32 v241, v232, v241, s60
	v_lshrrev_b32_e32 v241, 16, v241
	v_and_or_b32 v50, v240, s33, v241
	v_bfe_u32 v240, v235, 16, 1
	v_add3_u32 v240, v235, v240, s60
	v_bfe_u32 v241, v234, 16, 1
	v_add3_u32 v241, v234, v241, s60
	v_lshrrev_b32_e32 v241, 16, v241
	v_and_or_b32 v51, v240, s33, v241
	v_bfe_u32 v240, v239, 16, 1
	v_add3_u32 v240, v239, v240, s60
	v_bfe_u32 v241, v238, 16, 1
	v_add3_u32 v241, v238, v241, s60
	v_lshrrev_b32_e32 v241, 16, v241
	v_and_or_b32 v52, v240, s33, v241
	v_bfe_u32 v240, v237, 16, 1
	v_add3_u32 v240, v237, v240, s60
	v_bfe_u32 v241, v236, 16, 1
	v_add3_u32 v241, v236, v241, s60
	v_lshrrev_b32_e32 v241, 16, v241
	v_and_or_b32 v53, v240, s33, v241
	v_ashrrev_i32_e32 v45, 31, v44
	v_lshlrev_b64 v[46:47], 7, v[44:45]
	v_lshl_add_u64 v[46:47], v[42:43], 0, v[46:47]
	global_store_dwordx4 v[46:47], v[50:53], off
.LBB0_1311:
	s_or_b64 exec, exec, s[34:35]
	v_add_u32_e32 v46, 8, v44
	v_cmp_gt_i32_e32 vcc, s3, v46
	s_and_saveexec_b64 s[34:35], vcc
	s_cbranch_execz .LBB0_1313
	ds_read2_b32 v[232:233], v49 offset0:136 offset1:201
	ds_read2_b32 v[234:235], v48 offset0:10 offset1:75
	ds_read2_b32 v[236:237], v0 offset0:14 offset1:79
	ds_read2_b32 v[238:239], v48 offset0:140 offset1:205
	s_waitcnt lgkmcnt(0)
	v_bfe_u32 v240, v233, 16, 1
	v_add3_u32 v240, v233, v240, s60
	v_bfe_u32 v241, v232, 16, 1
	v_add3_u32 v241, v232, v241, s60
	v_lshrrev_b32_e32 v241, 16, v241
	v_and_or_b32 v50, v240, s33, v241
	v_bfe_u32 v240, v235, 16, 1
	v_add3_u32 v240, v235, v240, s60
	v_bfe_u32 v241, v234, 16, 1
	v_add3_u32 v241, v234, v241, s60
	v_lshrrev_b32_e32 v241, 16, v241
	v_and_or_b32 v51, v240, s33, v241
	v_bfe_u32 v240, v239, 16, 1
	v_add3_u32 v240, v239, v240, s60
	v_bfe_u32 v241, v238, 16, 1
	v_add3_u32 v241, v238, v241, s60
	v_lshrrev_b32_e32 v241, 16, v241
	v_and_or_b32 v52, v240, s33, v241
	v_bfe_u32 v240, v237, 16, 1
	v_add3_u32 v240, v237, v240, s60
	v_bfe_u32 v241, v236, 16, 1
	v_add3_u32 v241, v236, v241, s60
	v_lshrrev_b32_e32 v241, 16, v241
	v_and_or_b32 v53, v240, s33, v241
	v_ashrrev_i32_e32 v47, 31, v46
	v_lshlrev_b64 v[46:47], 7, v[46:47]
	v_lshl_add_u64 v[46:47], v[42:43], 0, v[46:47]
	global_store_dwordx4 v[46:47], v[50:53], off
.LBB0_1313:
	s_or_b64 exec, exec, s[34:35]
	v_add_u32_e32 v46, 16, v44
	v_cmp_gt_i32_e32 vcc, s3, v46
	s_and_saveexec_b64 s[34:35], vcc
	s_mov_b32 s46, s18
	s_cbranch_execz .LBB0_1315
	ds_read2_b32 v[232:233], v49 offset0:144 offset1:209
	ds_read2_b32 v[234:235], v48 offset0:18 offset1:83
	ds_read2_b32 v[236:237], v0 offset0:22 offset1:87
	ds_read2_b32 v[238:239], v48 offset0:148 offset1:213
	s_waitcnt lgkmcnt(0)
	v_bfe_u32 v240, v233, 16, 1
	v_add3_u32 v240, v233, v240, s60
	v_bfe_u32 v241, v232, 16, 1
	v_add3_u32 v241, v232, v241, s60
	v_lshrrev_b32_e32 v241, 16, v241
	v_and_or_b32 v50, v240, s33, v241
	v_bfe_u32 v240, v235, 16, 1
	v_add3_u32 v240, v235, v240, s60
	v_bfe_u32 v241, v234, 16, 1
	v_add3_u32 v241, v234, v241, s60
	v_lshrrev_b32_e32 v241, 16, v241
	v_and_or_b32 v51, v240, s33, v241
	v_bfe_u32 v240, v239, 16, 1
	v_add3_u32 v240, v239, v240, s60
	v_bfe_u32 v241, v238, 16, 1
	v_add3_u32 v241, v238, v241, s60
	v_lshrrev_b32_e32 v241, 16, v241
	v_and_or_b32 v52, v240, s33, v241
	v_bfe_u32 v240, v237, 16, 1
	v_add3_u32 v240, v237, v240, s60
	v_bfe_u32 v241, v236, 16, 1
	v_add3_u32 v241, v236, v241, s60
	v_lshrrev_b32_e32 v241, 16, v241
	v_and_or_b32 v53, v240, s33, v241
	v_ashrrev_i32_e32 v47, 31, v46
	v_lshlrev_b64 v[46:47], 7, v[46:47]
	v_lshl_add_u64 v[46:47], v[42:43], 0, v[46:47]
	global_store_dwordx4 v[46:47], v[50:53], off
.LBB0_1315:
	s_or_b64 exec, exec, s[34:35]
	v_add_u32_e32 v46, 24, v44
	v_cmp_gt_i32_e32 vcc, s3, v46
	s_and_saveexec_b64 s[34:35], vcc
	s_cbranch_execz .LBB0_1317
	ds_read2_b32 v[232:233], v49 offset0:152 offset1:217
	ds_read2_b32 v[234:235], v48 offset0:26 offset1:91
	ds_read2_b32 v[236:237], v0 offset0:30 offset1:95
	ds_read2_b32 v[238:239], v48 offset0:156 offset1:221
	s_waitcnt lgkmcnt(0)
	v_bfe_u32 v240, v233, 16, 1
	v_add3_u32 v240, v233, v240, s60
	v_bfe_u32 v241, v232, 16, 1
	v_add3_u32 v241, v232, v241, s60
	v_lshrrev_b32_e32 v241, 16, v241
	v_and_or_b32 v50, v240, s33, v241
	v_bfe_u32 v240, v235, 16, 1
	v_add3_u32 v240, v235, v240, s60
	v_bfe_u32 v241, v234, 16, 1
	v_add3_u32 v241, v234, v241, s60
	v_lshrrev_b32_e32 v241, 16, v241
	v_and_or_b32 v51, v240, s33, v241
	v_bfe_u32 v240, v239, 16, 1
	v_add3_u32 v240, v239, v240, s60
	v_bfe_u32 v241, v238, 16, 1
	v_add3_u32 v241, v238, v241, s60
	v_lshrrev_b32_e32 v241, 16, v241
	v_and_or_b32 v52, v240, s33, v241
	v_bfe_u32 v240, v237, 16, 1
	v_add3_u32 v240, v237, v240, s60
	v_bfe_u32 v241, v236, 16, 1
	v_add3_u32 v241, v236, v241, s60
	v_lshrrev_b32_e32 v241, 16, v241
	v_and_or_b32 v53, v240, s33, v241
	v_ashrrev_i32_e32 v47, 31, v46
	v_lshlrev_b64 v[46:47], 7, v[46:47]
	v_lshl_add_u64 v[46:47], v[42:43], 0, v[46:47]
	global_store_dwordx4 v[46:47], v[50:53], off
.LBB0_1317:
	s_or_b64 exec, exec, s[34:35]
	v_add_u32_e32 v46, 32, v44
	v_cmp_gt_i32_e32 vcc, s3, v46
	s_and_saveexec_b64 s[34:35], vcc
	s_cbranch_execz .LBB0_1319
	ds_read2_b32 v[232:233], v49 offset0:160 offset1:225
	ds_read2_b32 v[234:235], v48 offset0:34 offset1:99
	ds_read2_b32 v[236:237], v0 offset0:38 offset1:103
	ds_read2_b32 v[238:239], v48 offset0:164 offset1:229
	s_waitcnt lgkmcnt(0)
	v_bfe_u32 v240, v233, 16, 1
	v_add3_u32 v240, v233, v240, s60
	v_bfe_u32 v241, v232, 16, 1
	v_add3_u32 v241, v232, v241, s60
	v_lshrrev_b32_e32 v241, 16, v241
	v_and_or_b32 v50, v240, s33, v241
	v_bfe_u32 v240, v235, 16, 1
	v_add3_u32 v240, v235, v240, s60
	v_bfe_u32 v241, v234, 16, 1
	v_add3_u32 v241, v234, v241, s60
	v_lshrrev_b32_e32 v241, 16, v241
	v_and_or_b32 v51, v240, s33, v241
	v_bfe_u32 v240, v239, 16, 1
	v_add3_u32 v240, v239, v240, s60
	v_bfe_u32 v241, v238, 16, 1
	v_add3_u32 v241, v238, v241, s60
	v_lshrrev_b32_e32 v241, 16, v241
	v_and_or_b32 v52, v240, s33, v241
	v_bfe_u32 v240, v237, 16, 1
	v_add3_u32 v240, v237, v240, s60
	v_bfe_u32 v241, v236, 16, 1
	v_add3_u32 v241, v236, v241, s60
	v_lshrrev_b32_e32 v241, 16, v241
	v_and_or_b32 v53, v240, s33, v241
	v_ashrrev_i32_e32 v47, 31, v46
	v_lshlrev_b64 v[46:47], 7, v[46:47]
	v_lshl_add_u64 v[46:47], v[42:43], 0, v[46:47]
	global_store_dwordx4 v[46:47], v[50:53], off
.LBB0_1319:
	s_or_b64 exec, exec, s[34:35]
	v_add_u32_e32 v46, 40, v44
	v_cmp_gt_i32_e32 vcc, s3, v46
	s_and_saveexec_b64 s[34:35], vcc
	s_cbranch_execz .LBB0_1321
	ds_read2_b32 v[232:233], v49 offset0:168 offset1:233
	ds_read2_b32 v[234:235], v48 offset0:42 offset1:107
	ds_read2_b32 v[236:237], v0 offset0:46 offset1:111
	ds_read2_b32 v[238:239], v48 offset0:172 offset1:237
	s_waitcnt lgkmcnt(0)
	v_bfe_u32 v240, v233, 16, 1
	v_add3_u32 v240, v233, v240, s60
	v_bfe_u32 v241, v232, 16, 1
	v_add3_u32 v241, v232, v241, s60
	v_lshrrev_b32_e32 v241, 16, v241
	v_and_or_b32 v50, v240, s33, v241
	v_bfe_u32 v240, v235, 16, 1
	v_add3_u32 v240, v235, v240, s60
	v_bfe_u32 v241, v234, 16, 1
	v_add3_u32 v241, v234, v241, s60
	v_lshrrev_b32_e32 v241, 16, v241
	v_and_or_b32 v51, v240, s33, v241
	v_bfe_u32 v240, v239, 16, 1
	v_add3_u32 v240, v239, v240, s60
	v_bfe_u32 v241, v238, 16, 1
	v_add3_u32 v241, v238, v241, s60
	v_lshrrev_b32_e32 v241, 16, v241
	v_and_or_b32 v52, v240, s33, v241
	v_bfe_u32 v240, v237, 16, 1
	v_add3_u32 v240, v237, v240, s60
	v_bfe_u32 v241, v236, 16, 1
	v_add3_u32 v241, v236, v241, s60
	v_lshrrev_b32_e32 v241, 16, v241
	v_and_or_b32 v53, v240, s33, v241
	v_ashrrev_i32_e32 v47, 31, v46
	v_lshlrev_b64 v[46:47], 7, v[46:47]
	v_lshl_add_u64 v[46:47], v[42:43], 0, v[46:47]
	global_store_dwordx4 v[46:47], v[50:53], off
.LBB0_1321:
	s_or_b64 exec, exec, s[34:35]
	v_add_u32_e32 v46, 48, v44
	v_cmp_gt_i32_e32 vcc, s3, v46
	s_and_saveexec_b64 s[34:35], vcc
	s_cbranch_execz .LBB0_1323
	ds_read2_b32 v[232:233], v49 offset0:176 offset1:241
	ds_read2_b32 v[234:235], v48 offset0:50 offset1:115
	ds_read2_b32 v[236:237], v0 offset0:54 offset1:119
	ds_read2_b32 v[238:239], v48 offset0:180 offset1:245
	s_waitcnt lgkmcnt(0)
	v_bfe_u32 v240, v233, 16, 1
	v_add3_u32 v240, v233, v240, s60
	v_bfe_u32 v241, v232, 16, 1
	v_add3_u32 v241, v232, v241, s60
	v_lshrrev_b32_e32 v241, 16, v241
	v_and_or_b32 v50, v240, s33, v241
	v_bfe_u32 v240, v235, 16, 1
	v_add3_u32 v240, v235, v240, s60
	v_bfe_u32 v241, v234, 16, 1
	v_add3_u32 v241, v234, v241, s60
	v_lshrrev_b32_e32 v241, 16, v241
	v_and_or_b32 v51, v240, s33, v241
	v_bfe_u32 v240, v239, 16, 1
	v_add3_u32 v240, v239, v240, s60
	v_bfe_u32 v241, v238, 16, 1
	v_add3_u32 v241, v238, v241, s60
	v_lshrrev_b32_e32 v241, 16, v241
	v_and_or_b32 v52, v240, s33, v241
	v_bfe_u32 v240, v237, 16, 1
	v_add3_u32 v240, v237, v240, s60
	v_bfe_u32 v241, v236, 16, 1
	v_add3_u32 v241, v236, v241, s60
	v_lshrrev_b32_e32 v241, 16, v241
	v_and_or_b32 v53, v240, s33, v241
	v_ashrrev_i32_e32 v47, 31, v46
	v_lshlrev_b64 v[46:47], 7, v[46:47]
	v_lshl_add_u64 v[46:47], v[42:43], 0, v[46:47]
	global_store_dwordx4 v[46:47], v[50:53], off
.LBB0_1323:
	s_or_b64 exec, exec, s[34:35]
	v_add_u32_e32 v44, 56, v44
	v_cmp_gt_i32_e32 vcc, s3, v44
	s_and_saveexec_b64 s[34:35], vcc
	s_cbranch_execz .LBB0_1325
	ds_read2_b32 v[232:233], v49 offset0:184 offset1:249
	ds_read2_b32 v[234:235], v48 offset0:58 offset1:123
	ds_read2_b32 v[236:237], v48 offset0:188 offset1:253
	ds_read2_b32 v[238:239], v0 offset0:62 offset1:127
	s_waitcnt lgkmcnt(0)
	v_bfe_u32 v240, v233, 16, 1
	v_add3_u32 v240, v233, v240, s60
	v_bfe_u32 v241, v232, 16, 1
	v_add3_u32 v241, v232, v241, s60
	v_lshrrev_b32_e32 v241, 16, v241
	v_and_or_b32 v46, v240, s33, v241
	v_bfe_u32 v240, v235, 16, 1
	v_add3_u32 v240, v235, v240, s60
	v_bfe_u32 v241, v234, 16, 1
	v_add3_u32 v241, v234, v241, s60
	v_lshrrev_b32_e32 v241, 16, v241
	v_and_or_b32 v47, v240, s33, v241
	v_bfe_u32 v240, v237, 16, 1
	v_add3_u32 v240, v237, v240, s60
	v_bfe_u32 v241, v236, 16, 1
	v_add3_u32 v241, v236, v241, s60
	v_lshrrev_b32_e32 v241, 16, v241
	v_and_or_b32 v48, v240, s33, v241
	v_bfe_u32 v240, v239, 16, 1
	v_add3_u32 v240, v239, v240, s60
	v_bfe_u32 v241, v238, 16, 1
	v_add3_u32 v241, v238, v241, s60
	v_lshrrev_b32_e32 v241, 16, v241
	v_and_or_b32 v49, v240, s33, v241
	v_ashrrev_i32_e32 v45, 31, v44
	v_lshlrev_b64 v[44:45], 7, v[44:45]
	v_lshl_add_u64 v[42:43], v[42:43], 0, v[44:45]
	global_store_dwordx4 v[42:43], v[46:49], off

.LBB0_1360:
	s_or_b64 exec, exec, s[34:35]
	s_movk_i32 s1, 0x104
	v_mul_lo_u32 v116, v148, s1
	v_readlane_b32 s3, v251, 59
	s_lshl_b32 s0, s0, 1
	s_nop 0
	v_add3_u32 v0, s3, v0, v116
	v_add_u32_e32 v116, 0x2e00, v0
	s_waitcnt vmcnt(0)
	ds_write2_b32 v116, v42, v43 offset1:1
	v_add_u32_e32 v42, 0x2e08, v0
	ds_write2_b32 v42, v44, v45 offset1:1
	v_add_u32_e32 v42, 0x3210, v0
	ds_write2_b32 v42, v46, v47 offset1:1
	v_add_u32_e32 v42, 0x3218, v0
	ds_write2_b32 v42, v48, v49 offset1:1
	v_add_u32_e32 v42, 0x3620, v0
	ds_write2_b32 v42, v54, v55 offset1:1
	v_add_u32_e32 v42, 0x3628, v0
	ds_write2_b32 v42, v56, v57 offset1:1
	v_add_u32_e32 v42, 0x3a30, v0
	ds_write2_b32 v42, v50, v51 offset1:1
	v_add_u32_e32 v42, 0x3a38, v0
	ds_write2_b32 v42, v52, v53 offset1:1
	v_add_u32_e32 v42, 0x3e40, v0
	ds_write2_b32 v42, v62, v63 offset1:1
	v_add_u32_e32 v42, 0x3e48, v0
	ds_write2_b32 v42, v64, v65 offset1:1
	v_add_u32_e32 v42, 0x4250, v0
	ds_write2_b32 v42, v58, v59 offset1:1
	v_add_u32_e32 v42, 0x4258, v0
	ds_write2_b32 v42, v60, v61 offset1:1
	v_add_u32_e32 v42, 0x4660, v0
	ds_write2_b32 v42, v70, v71 offset1:1
	v_add_u32_e32 v42, 0x4668, v0
	ds_write2_b32 v42, v72, v73 offset1:1
	v_add_u32_e32 v42, 0x4a70, v0
	ds_write2_b32 v42, v66, v67 offset1:1
	v_add_u32_e32 v42, 0x4a78, v0
	ds_write2_b32 v42, v68, v69 offset1:1
	v_add_u32_e32 v42, 0x4e80, v0
	ds_write2_b32 v42, v78, v79 offset1:1
	v_add_u32_e32 v42, 0x4e88, v0
	ds_write2_b32 v42, v80, v81 offset1:1
	v_add_u32_e32 v42, 0x5290, v0
	ds_write2_b32 v42, v74, v75 offset1:1
	v_add_u32_e32 v42, 0x5298, v0
	ds_write2_b32 v42, v76, v77 offset1:1
	v_add_u32_e32 v42, 0x56a0, v0
	ds_write2_b32 v42, v86, v87 offset1:1
	v_add_u32_e32 v42, 0x56a8, v0
	ds_write2_b32 v42, v88, v89 offset1:1
	v_add_u32_e32 v42, 0x5ab0, v0
	ds_write2_b32 v42, v82, v83 offset1:1
	v_add_u32_e32 v42, 0x5ab8, v0
	ds_write2_b32 v42, v84, v85 offset1:1
	v_add_u32_e32 v42, 0x5ec0, v0
	ds_write2_b32 v42, v94, v95 offset1:1
	v_add_u32_e32 v42, 0x5ec8, v0
	ds_write2_b32 v42, v96, v97 offset1:1
	v_add_u32_e32 v42, 0x62d0, v0
	ds_write2_b32 v42, v90, v91 offset1:1
	v_add_u32_e32 v42, 0x62d8, v0
	ds_write2_b32 v42, v92, v93 offset1:1
	v_add_u32_e32 v42, 0x66e0, v0
	ds_write2_b32 v42, v102, v103 offset1:1
	v_add_u32_e32 v42, 0x66e8, v0
	ds_write2_b32 v42, v104, v105 offset1:1
	v_add_u32_e32 v42, 0x6af0, v0
	v_add_u32_e32 v0, 0x6af8, v0
	ds_write2_b32 v0, v100, v101 offset1:1
	v_lshlrev_b32_e32 v0, 3, v115
	ds_write2_b32 v42, v98, v99 offset1:1
	v_and_b32_e32 v0, 56, v0
	v_mov_b32_e32 v42, s3
	v_mad_u32_u24 v46, v0, s1, v42
	v_readlane_b32 s1, v250, 12
	s_add_u32 s0, s1, s0
	v_readlane_b32 s1, v250, 16
	s_waitcnt lgkmcnt(0)
	v_ashrrev_i32_e32 v45, 3, v115
	s_addc_u32 s1, s1, 0
	v_lshlrev_b32_e32 v0, 1, v0
	v_lshl_add_u64 v[42:43], s[0:1], 0, v[0:1]
	v_add_u32_e32 v44, s30, v45
	s_movk_i32 s0, 0x800
	v_lshl_add_u32 v0, v45, 2, v46
	v_cmp_gt_i32_e32 vcc, s0, v44
	v_add_u32_e32 v49, 0x2c00, v0
	v_add_u32_e32 v48, 0x3000, v0
	v_add_u32_e32 v0, 0x3400, v0
	s_and_saveexec_b64 s[30:31], vcc
	s_cbranch_execz .LBB0_1362
	ds_read2_b32 v[232:233], v49 offset0:128 offset1:193
	ds_read2_b32 v[234:235], v48 offset0:2 offset1:67
	ds_read2_b32 v[236:237], v0 offset0:6 offset1:71
	ds_read2_b32 v[238:239], v48 offset0:132 offset1:197
	s_waitcnt lgkmcnt(0)
	v_bfe_u32 v240, v233, 16, 1
	v_add3_u32 v240, v233, v240, s60
	v_bfe_u32 v241, v232, 16, 1
	v_add3_u32 v241, v232, v241, s60
	v_lshrrev_b32_e32 v241, 16, v241
	v_and_or_b32 v50, v240, s33, v241
	v_bfe_u32 v240, v235, 16, 1
	v_add3_u32 v240, v235, v240, s60
	v_bfe_u32 v241, v234, 16, 1
	v_add3_u32 v241, v234, v241, s60
	v_lshrrev_b32_e32 v241, 16, v241
	v_and_or_b32 v51, v240, s33, v241
	v_bfe_u32 v240, v239, 16, 1
	v_add3_u32 v240, v239, v240, s60
	v_bfe_u32 v241, v238, 16, 1
	v_add3_u32 v241, v238, v241, s60
	v_lshrrev_b32_e32 v241, 16, v241
	v_and_or_b32 v52, v240, s33, v241
	v_bfe_u32 v240, v237, 16, 1
	v_add3_u32 v240, v237, v240, s60
	v_bfe_u32 v241, v236, 16, 1
	v_add3_u32 v241, v236, v241, s60
	v_lshrrev_b32_e32 v241, 16, v241
	v_and_or_b32 v53, v240, s33, v241
	v_ashrrev_i32_e32 v45, 31, v44
	v_lshlrev_b64 v[46:47], 10, v[44:45]
	v_lshl_add_u64 v[46:47], v[42:43], 0, v[46:47]
	global_store_dwordx4 v[46:47], v[50:53], off
.LBB0_1362:
	s_or_b64 exec, exec, s[30:31]
	v_add_u32_e32 v46, 8, v44
	v_cmp_gt_i32_e32 vcc, s0, v46
	s_and_saveexec_b64 s[30:31], vcc
	s_cbranch_execz .LBB0_1364
	ds_read2_b32 v[232:233], v49 offset0:136 offset1:201
	ds_read2_b32 v[234:235], v48 offset0:10 offset1:75
	ds_read2_b32 v[236:237], v0 offset0:14 offset1:79
	ds_read2_b32 v[238:239], v48 offset0:140 offset1:205
	s_waitcnt lgkmcnt(0)
	v_bfe_u32 v240, v233, 16, 1
	v_add3_u32 v240, v233, v240, s60
	v_bfe_u32 v241, v232, 16, 1
	v_add3_u32 v241, v232, v241, s60
	v_lshrrev_b32_e32 v241, 16, v241
	v_and_or_b32 v50, v240, s33, v241
	v_bfe_u32 v240, v235, 16, 1
	v_add3_u32 v240, v235, v240, s60
	v_bfe_u32 v241, v234, 16, 1
	v_add3_u32 v241, v234, v241, s60
	v_lshrrev_b32_e32 v241, 16, v241
	v_and_or_b32 v51, v240, s33, v241
	v_bfe_u32 v240, v239, 16, 1
	v_add3_u32 v240, v239, v240, s60
	v_bfe_u32 v241, v238, 16, 1
	v_add3_u32 v241, v238, v241, s60
	v_lshrrev_b32_e32 v241, 16, v241
	v_and_or_b32 v52, v240, s33, v241
	v_bfe_u32 v240, v237, 16, 1
	v_add3_u32 v240, v237, v240, s60
	v_bfe_u32 v241, v236, 16, 1
	v_add3_u32 v241, v236, v241, s60
	v_lshrrev_b32_e32 v241, 16, v241
	v_and_or_b32 v53, v240, s33, v241
	v_ashrrev_i32_e32 v47, 31, v46
	v_lshlrev_b64 v[46:47], 10, v[46:47]
	v_lshl_add_u64 v[46:47], v[42:43], 0, v[46:47]
	global_store_dwordx4 v[46:47], v[50:53], off
.LBB0_1364:
	s_or_b64 exec, exec, s[30:31]
	v_add_u32_e32 v46, 16, v44
	v_cmp_gt_i32_e32 vcc, s0, v46
	s_and_saveexec_b64 s[30:31], vcc
	s_cbranch_execz .LBB0_1366
	ds_read2_b32 v[232:233], v49 offset0:144 offset1:209
	ds_read2_b32 v[234:235], v48 offset0:18 offset1:83
	ds_read2_b32 v[236:237], v0 offset0:22 offset1:87
	ds_read2_b32 v[238:239], v48 offset0:148 offset1:213
	s_waitcnt lgkmcnt(0)
	v_bfe_u32 v240, v233, 16, 1
	v_add3_u32 v240, v233, v240, s60
	v_bfe_u32 v241, v232, 16, 1
	v_add3_u32 v241, v232, v241, s60
	v_lshrrev_b32_e32 v241, 16, v241
	v_and_or_b32 v50, v240, s33, v241
	v_bfe_u32 v240, v235, 16, 1
	v_add3_u32 v240, v235, v240, s60
	v_bfe_u32 v241, v234, 16, 1
	v_add3_u32 v241, v234, v241, s60
	v_lshrrev_b32_e32 v241, 16, v241
	v_and_or_b32 v51, v240, s33, v241
	v_bfe_u32 v240, v239, 16, 1
	v_add3_u32 v240, v239, v240, s60
	v_bfe_u32 v241, v238, 16, 1
	v_add3_u32 v241, v238, v241, s60
	v_lshrrev_b32_e32 v241, 16, v241
	v_and_or_b32 v52, v240, s33, v241
	v_bfe_u32 v240, v237, 16, 1
	v_add3_u32 v240, v237, v240, s60
	v_bfe_u32 v241, v236, 16, 1
	v_add3_u32 v241, v236, v241, s60
	v_lshrrev_b32_e32 v241, 16, v241
	v_and_or_b32 v53, v240, s33, v241
	v_ashrrev_i32_e32 v47, 31, v46
	v_lshlrev_b64 v[46:47], 10, v[46:47]
	v_lshl_add_u64 v[46:47], v[42:43], 0, v[46:47]
	global_store_dwordx4 v[46:47], v[50:53], off
.LBB0_1366:
	s_or_b64 exec, exec, s[30:31]
	v_add_u32_e32 v46, 24, v44
	v_cmp_gt_i32_e32 vcc, s0, v46
	s_and_saveexec_b64 s[30:31], vcc
	s_cbranch_execz .LBB0_1368
	ds_read2_b32 v[232:233], v49 offset0:152 offset1:217
	ds_read2_b32 v[234:235], v48 offset0:26 offset1:91
	ds_read2_b32 v[236:237], v0 offset0:30 offset1:95
	ds_read2_b32 v[238:239], v48 offset0:156 offset1:221
	s_waitcnt lgkmcnt(0)
	v_bfe_u32 v240, v233, 16, 1
	v_add3_u32 v240, v233, v240, s60
	v_bfe_u32 v241, v232, 16, 1
	v_add3_u32 v241, v232, v241, s60
	v_lshrrev_b32_e32 v241, 16, v241
	v_and_or_b32 v50, v240, s33, v241
	v_bfe_u32 v240, v235, 16, 1
	v_add3_u32 v240, v235, v240, s60
	v_bfe_u32 v241, v234, 16, 1
	v_add3_u32 v241, v234, v241, s60
	v_lshrrev_b32_e32 v241, 16, v241
	v_and_or_b32 v51, v240, s33, v241
	v_bfe_u32 v240, v239, 16, 1
	v_add3_u32 v240, v239, v240, s60
	v_bfe_u32 v241, v238, 16, 1
	v_add3_u32 v241, v238, v241, s60
	v_lshrrev_b32_e32 v241, 16, v241
	v_and_or_b32 v52, v240, s33, v241
	v_bfe_u32 v240, v237, 16, 1
	v_add3_u32 v240, v237, v240, s60
	v_bfe_u32 v241, v236, 16, 1
	v_add3_u32 v241, v236, v241, s60
	v_lshrrev_b32_e32 v241, 16, v241
	v_and_or_b32 v53, v240, s33, v241
	v_ashrrev_i32_e32 v47, 31, v46
	v_lshlrev_b64 v[46:47], 10, v[46:47]
	v_lshl_add_u64 v[46:47], v[42:43], 0, v[46:47]
	global_store_dwordx4 v[46:47], v[50:53], off
.LBB0_1368:
	s_or_b64 exec, exec, s[30:31]
	v_add_u32_e32 v46, 32, v44
	v_cmp_gt_i32_e32 vcc, s0, v46
	s_and_saveexec_b64 s[30:31], vcc
	s_cbranch_execz .LBB0_1370
	ds_read2_b32 v[232:233], v49 offset0:160 offset1:225
	ds_read2_b32 v[234:235], v48 offset0:34 offset1:99
	ds_read2_b32 v[236:237], v0 offset0:38 offset1:103
	ds_read2_b32 v[238:239], v48 offset0:164 offset1:229
	s_waitcnt lgkmcnt(0)
	v_bfe_u32 v240, v233, 16, 1
	v_add3_u32 v240, v233, v240, s60
	v_bfe_u32 v241, v232, 16, 1
	v_add3_u32 v241, v232, v241, s60
	v_lshrrev_b32_e32 v241, 16, v241
	v_and_or_b32 v50, v240, s33, v241
	v_bfe_u32 v240, v235, 16, 1
	v_add3_u32 v240, v235, v240, s60
	v_bfe_u32 v241, v234, 16, 1
	v_add3_u32 v241, v234, v241, s60
	v_lshrrev_b32_e32 v241, 16, v241
	v_and_or_b32 v51, v240, s33, v241
	v_bfe_u32 v240, v239, 16, 1
	v_add3_u32 v240, v239, v240, s60
	v_bfe_u32 v241, v238, 16, 1
	v_add3_u32 v241, v238, v241, s60
	v_lshrrev_b32_e32 v241, 16, v241
	v_and_or_b32 v52, v240, s33, v241
	v_bfe_u32 v240, v237, 16, 1
	v_add3_u32 v240, v237, v240, s60
	v_bfe_u32 v241, v236, 16, 1
	v_add3_u32 v241, v236, v241, s60
	v_lshrrev_b32_e32 v241, 16, v241
	v_and_or_b32 v53, v240, s33, v241
	v_ashrrev_i32_e32 v47, 31, v46
	v_lshlrev_b64 v[46:47], 10, v[46:47]
	v_lshl_add_u64 v[46:47], v[42:43], 0, v[46:47]
	global_store_dwordx4 v[46:47], v[50:53], off
.LBB0_1370:
	s_or_b64 exec, exec, s[30:31]
	v_add_u32_e32 v46, 40, v44
	v_cmp_gt_i32_e32 vcc, s0, v46
	s_and_saveexec_b64 s[30:31], vcc
	s_cbranch_execz .LBB0_1372
	ds_read2_b32 v[232:233], v49 offset0:168 offset1:233
	ds_read2_b32 v[234:235], v48 offset0:42 offset1:107
	ds_read2_b32 v[236:237], v0 offset0:46 offset1:111
	ds_read2_b32 v[238:239], v48 offset0:172 offset1:237
	s_waitcnt lgkmcnt(0)
	v_bfe_u32 v240, v233, 16, 1
	v_add3_u32 v240, v233, v240, s60
	v_bfe_u32 v241, v232, 16, 1
	v_add3_u32 v241, v232, v241, s60
	v_lshrrev_b32_e32 v241, 16, v241
	v_and_or_b32 v50, v240, s33, v241
	v_bfe_u32 v240, v235, 16, 1
	v_add3_u32 v240, v235, v240, s60
	v_bfe_u32 v241, v234, 16, 1
	v_add3_u32 v241, v234, v241, s60
	v_lshrrev_b32_e32 v241, 16, v241
	v_and_or_b32 v51, v240, s33, v241
	v_bfe_u32 v240, v239, 16, 1
	v_add3_u32 v240, v239, v240, s60
	v_bfe_u32 v241, v238, 16, 1
	v_add3_u32 v241, v238, v241, s60
	v_lshrrev_b32_e32 v241, 16, v241
	v_and_or_b32 v52, v240, s33, v241
	v_bfe_u32 v240, v237, 16, 1
	v_add3_u32 v240, v237, v240, s60
	v_bfe_u32 v241, v236, 16, 1
	v_add3_u32 v241, v236, v241, s60
	v_lshrrev_b32_e32 v241, 16, v241
	v_and_or_b32 v53, v240, s33, v241
	v_ashrrev_i32_e32 v47, 31, v46
	v_lshlrev_b64 v[46:47], 10, v[46:47]
	v_lshl_add_u64 v[46:47], v[42:43], 0, v[46:47]
	global_store_dwordx4 v[46:47], v[50:53], off
.LBB0_1372:
	s_or_b64 exec, exec, s[30:31]
	v_add_u32_e32 v46, 48, v44
	v_cmp_gt_i32_e32 vcc, s0, v46
	s_and_saveexec_b64 s[30:31], vcc
	s_cbranch_execz .LBB0_1374
	ds_read2_b32 v[232:233], v49 offset0:176 offset1:241
	ds_read2_b32 v[234:235], v48 offset0:50 offset1:115
	ds_read2_b32 v[236:237], v0 offset0:54 offset1:119
	ds_read2_b32 v[238:239], v48 offset0:180 offset1:245
	s_waitcnt lgkmcnt(0)
	v_bfe_u32 v240, v233, 16, 1
	v_add3_u32 v240, v233, v240, s60
	v_bfe_u32 v241, v232, 16, 1
	v_add3_u32 v241, v232, v241, s60
	v_lshrrev_b32_e32 v241, 16, v241
	v_and_or_b32 v50, v240, s33, v241
	v_bfe_u32 v240, v235, 16, 1
	v_add3_u32 v240, v235, v240, s60
	v_bfe_u32 v241, v234, 16, 1
	v_add3_u32 v241, v234, v241, s60
	v_lshrrev_b32_e32 v241, 16, v241
	v_and_or_b32 v51, v240, s33, v241
	v_bfe_u32 v240, v239, 16, 1
	v_add3_u32 v240, v239, v240, s60
	v_bfe_u32 v241, v238, 16, 1
	v_add3_u32 v241, v238, v241, s60
	v_lshrrev_b32_e32 v241, 16, v241
	v_and_or_b32 v52, v240, s33, v241
	v_bfe_u32 v240, v237, 16, 1
	v_add3_u32 v240, v237, v240, s60
	v_bfe_u32 v241, v236, 16, 1
	v_add3_u32 v241, v236, v241, s60
	v_lshrrev_b32_e32 v241, 16, v241
	v_and_or_b32 v53, v240, s33, v241
	v_ashrrev_i32_e32 v47, 31, v46
	v_lshlrev_b64 v[46:47], 10, v[46:47]
	v_lshl_add_u64 v[46:47], v[42:43], 0, v[46:47]
	global_store_dwordx4 v[46:47], v[50:53], off
.LBB0_1374:
	s_or_b64 exec, exec, s[30:31]
	v_add_u32_e32 v44, 56, v44
	v_cmp_gt_i32_e32 vcc, s0, v44
	s_and_saveexec_b64 s[30:31], vcc
	s_cbranch_execz .LBB0_1376
	ds_read2_b32 v[232:233], v49 offset0:184 offset1:249
	ds_read2_b32 v[234:235], v48 offset0:58 offset1:123
	ds_read2_b32 v[236:237], v48 offset0:188 offset1:253
	ds_read2_b32 v[238:239], v0 offset0:62 offset1:127
	s_waitcnt lgkmcnt(0)
	v_bfe_u32 v240, v233, 16, 1
	v_add3_u32 v240, v233, v240, s60
	v_bfe_u32 v241, v232, 16, 1
	v_add3_u32 v241, v232, v241, s60
	v_lshrrev_b32_e32 v241, 16, v241
	v_and_or_b32 v46, v240, s33, v241
	v_bfe_u32 v240, v235, 16, 1
	v_add3_u32 v240, v235, v240, s60
	v_bfe_u32 v241, v234, 16, 1
	v_add3_u32 v241, v234, v241, s60
	v_lshrrev_b32_e32 v241, 16, v241
	v_and_or_b32 v47, v240, s33, v241
	v_bfe_u32 v240, v237, 16, 1
	v_add3_u32 v240, v237, v240, s60
	v_bfe_u32 v241, v236, 16, 1
	v_add3_u32 v241, v236, v241, s60
	v_lshrrev_b32_e32 v241, 16, v241
	v_and_or_b32 v48, v240, s33, v241
	v_bfe_u32 v240, v239, 16, 1
	v_add3_u32 v240, v239, v240, s60
	v_bfe_u32 v241, v238, 16, 1
	v_add3_u32 v241, v238, v241, s60
	v_lshrrev_b32_e32 v241, 16, v241
	v_and_or_b32 v49, v240, s33, v241
	v_ashrrev_i32_e32 v45, 31, v44
	v_lshlrev_b64 v[44:45], 10, v[44:45]
	v_lshl_add_u64 v[42:43], v[42:43], 0, v[44:45]
	global_store_dwordx4 v[42:43], v[46:49], off

.LBB0_1462:
	s_or_b64 exec, exec, s[30:31]
	s_movk_i32 s1, 0x104
	v_mul_lo_u32 v116, v148, s1
	v_readlane_b32 s3, v251, 59
	s_lshl_b32 s0, s0, 1
	s_nop 0
	v_add3_u32 v0, s3, v0, v116
	v_add_u32_e32 v116, 0x2e00, v0
	s_waitcnt vmcnt(0)
	ds_write2_b32 v116, v42, v43 offset1:1
	v_add_u32_e32 v42, 0x2e08, v0
	ds_write2_b32 v42, v44, v45 offset1:1
	v_add_u32_e32 v42, 0x3210, v0
	ds_write2_b32 v42, v46, v47 offset1:1
	v_add_u32_e32 v42, 0x3218, v0
	ds_write2_b32 v42, v48, v49 offset1:1
	v_add_u32_e32 v42, 0x3620, v0
	ds_write2_b32 v42, v54, v55 offset1:1
	v_add_u32_e32 v42, 0x3628, v0
	ds_write2_b32 v42, v56, v57 offset1:1
	v_add_u32_e32 v42, 0x3a30, v0
	ds_write2_b32 v42, v50, v51 offset1:1
	v_add_u32_e32 v42, 0x3a38, v0
	ds_write2_b32 v42, v52, v53 offset1:1
	v_add_u32_e32 v42, 0x3e40, v0
	ds_write2_b32 v42, v62, v63 offset1:1
	v_add_u32_e32 v42, 0x3e48, v0
	ds_write2_b32 v42, v64, v65 offset1:1
	v_add_u32_e32 v42, 0x4250, v0
	ds_write2_b32 v42, v58, v59 offset1:1
	v_add_u32_e32 v42, 0x4258, v0
	ds_write2_b32 v42, v60, v61 offset1:1
	v_add_u32_e32 v42, 0x4660, v0
	ds_write2_b32 v42, v70, v71 offset1:1
	v_add_u32_e32 v42, 0x4668, v0
	ds_write2_b32 v42, v72, v73 offset1:1
	v_add_u32_e32 v42, 0x4a70, v0
	ds_write2_b32 v42, v66, v67 offset1:1
	v_add_u32_e32 v42, 0x4a78, v0
	ds_write2_b32 v42, v68, v69 offset1:1
	v_add_u32_e32 v42, 0x4e80, v0
	ds_write2_b32 v42, v78, v79 offset1:1
	v_add_u32_e32 v42, 0x4e88, v0
	ds_write2_b32 v42, v80, v81 offset1:1
	v_add_u32_e32 v42, 0x5290, v0
	ds_write2_b32 v42, v74, v75 offset1:1
	v_add_u32_e32 v42, 0x5298, v0
	ds_write2_b32 v42, v76, v77 offset1:1
	v_add_u32_e32 v42, 0x56a0, v0
	ds_write2_b32 v42, v86, v87 offset1:1
	v_add_u32_e32 v42, 0x56a8, v0
	ds_write2_b32 v42, v88, v89 offset1:1
	v_add_u32_e32 v42, 0x5ab0, v0
	ds_write2_b32 v42, v82, v83 offset1:1
	v_add_u32_e32 v42, 0x5ab8, v0
	ds_write2_b32 v42, v84, v85 offset1:1
	v_add_u32_e32 v42, 0x5ec0, v0
	ds_write2_b32 v42, v94, v95 offset1:1
	v_add_u32_e32 v42, 0x5ec8, v0
	ds_write2_b32 v42, v96, v97 offset1:1
	v_add_u32_e32 v42, 0x62d0, v0
	ds_write2_b32 v42, v90, v91 offset1:1
	v_add_u32_e32 v42, 0x62d8, v0
	ds_write2_b32 v42, v92, v93 offset1:1
	v_add_u32_e32 v42, 0x66e0, v0
	ds_write2_b32 v42, v102, v103 offset1:1
	v_add_u32_e32 v42, 0x66e8, v0
	ds_write2_b32 v42, v104, v105 offset1:1
	v_add_u32_e32 v42, 0x6af0, v0
	v_add_u32_e32 v0, 0x6af8, v0
	ds_write2_b32 v0, v100, v101 offset1:1
	v_lshlrev_b32_e32 v0, 3, v115
	ds_write2_b32 v42, v98, v99 offset1:1
	v_and_b32_e32 v0, 56, v0
	v_mov_b32_e32 v42, s3
	v_mad_u32_u24 v46, v0, s1, v42
	v_readlane_b32 s1, v250, 32
	s_add_u32 s0, s1, s0
	v_readlane_b32 s1, v250, 8
	s_waitcnt lgkmcnt(0)
	v_ashrrev_i32_e32 v45, 3, v115
	s_addc_u32 s1, s1, 0
	v_lshlrev_b32_e32 v0, 1, v0
	v_lshl_add_u64 v[42:43], s[0:1], 0, v[0:1]
	v_add_u32_e32 v44, s24, v45
	s_movk_i32 s0, 0x200
	v_lshl_add_u32 v0, v45, 2, v46
	v_cmp_gt_i32_e32 vcc, s0, v44
	v_add_u32_e32 v49, 0x2c00, v0
	v_add_u32_e32 v48, 0x3000, v0
	v_add_u32_e32 v0, 0x3400, v0
	s_and_saveexec_b64 s[24:25], vcc
	s_cbranch_execz .LBB0_1464
	ds_read2_b32 v[232:233], v49 offset0:128 offset1:193
	ds_read2_b32 v[234:235], v48 offset0:2 offset1:67
	ds_read2_b32 v[236:237], v0 offset0:6 offset1:71
	ds_read2_b32 v[238:239], v48 offset0:132 offset1:197
	s_waitcnt lgkmcnt(0)
	v_bfe_u32 v240, v233, 16, 1
	v_add3_u32 v240, v233, v240, s60
	v_bfe_u32 v241, v232, 16, 1
	v_add3_u32 v241, v232, v241, s60
	v_lshrrev_b32_e32 v241, 16, v241
	v_and_or_b32 v50, v240, s33, v241
	v_bfe_u32 v240, v235, 16, 1
	v_add3_u32 v240, v235, v240, s60
	v_bfe_u32 v241, v234, 16, 1
	v_add3_u32 v241, v234, v241, s60
	v_lshrrev_b32_e32 v241, 16, v241
	v_and_or_b32 v51, v240, s33, v241
	v_bfe_u32 v240, v239, 16, 1
	v_add3_u32 v240, v239, v240, s60
	v_bfe_u32 v241, v238, 16, 1
	v_add3_u32 v241, v238, v241, s60
	v_lshrrev_b32_e32 v241, 16, v241
	v_and_or_b32 v52, v240, s33, v241
	v_bfe_u32 v240, v237, 16, 1
	v_add3_u32 v240, v237, v240, s60
	v_bfe_u32 v241, v236, 16, 1
	v_add3_u32 v241, v236, v241, s60
	v_lshrrev_b32_e32 v241, 16, v241
	v_and_or_b32 v53, v240, s33, v241
	v_ashrrev_i32_e32 v45, 31, v44
	v_lshlrev_b64 v[46:47], 12, v[44:45]
	v_lshl_add_u64 v[46:47], v[42:43], 0, v[46:47]
	global_store_dwordx4 v[46:47], v[50:53], off
.LBB0_1464:
	s_or_b64 exec, exec, s[24:25]
	v_add_u32_e32 v46, 8, v44
	v_cmp_gt_i32_e32 vcc, s0, v46
	s_and_saveexec_b64 s[24:25], vcc
	s_cbranch_execz .LBB0_1466
	ds_read2_b32 v[232:233], v49 offset0:136 offset1:201
	ds_read2_b32 v[234:235], v48 offset0:10 offset1:75
	ds_read2_b32 v[236:237], v0 offset0:14 offset1:79
	ds_read2_b32 v[238:239], v48 offset0:140 offset1:205
	s_waitcnt lgkmcnt(0)
	v_bfe_u32 v240, v233, 16, 1
	v_add3_u32 v240, v233, v240, s60
	v_bfe_u32 v241, v232, 16, 1
	v_add3_u32 v241, v232, v241, s60
	v_lshrrev_b32_e32 v241, 16, v241
	v_and_or_b32 v50, v240, s33, v241
	v_bfe_u32 v240, v235, 16, 1
	v_add3_u32 v240, v235, v240, s60
	v_bfe_u32 v241, v234, 16, 1
	v_add3_u32 v241, v234, v241, s60
	v_lshrrev_b32_e32 v241, 16, v241
	v_and_or_b32 v51, v240, s33, v241
	v_bfe_u32 v240, v239, 16, 1
	v_add3_u32 v240, v239, v240, s60
	v_bfe_u32 v241, v238, 16, 1
	v_add3_u32 v241, v238, v241, s60
	v_lshrrev_b32_e32 v241, 16, v241
	v_and_or_b32 v52, v240, s33, v241
	v_bfe_u32 v240, v237, 16, 1
	v_add3_u32 v240, v237, v240, s60
	v_bfe_u32 v241, v236, 16, 1
	v_add3_u32 v241, v236, v241, s60
	v_lshrrev_b32_e32 v241, 16, v241
	v_and_or_b32 v53, v240, s33, v241
	v_ashrrev_i32_e32 v47, 31, v46
	v_lshlrev_b64 v[46:47], 12, v[46:47]
	v_lshl_add_u64 v[46:47], v[42:43], 0, v[46:47]
	global_store_dwordx4 v[46:47], v[50:53], off
.LBB0_1466:
	s_or_b64 exec, exec, s[24:25]
	v_add_u32_e32 v46, 16, v44
	v_cmp_gt_i32_e32 vcc, s0, v46
	s_and_saveexec_b64 s[24:25], vcc
	s_cbranch_execz .LBB0_1468
	ds_read2_b32 v[232:233], v49 offset0:144 offset1:209
	ds_read2_b32 v[234:235], v48 offset0:18 offset1:83
	ds_read2_b32 v[236:237], v0 offset0:22 offset1:87
	ds_read2_b32 v[238:239], v48 offset0:148 offset1:213
	s_waitcnt lgkmcnt(0)
	v_bfe_u32 v240, v233, 16, 1
	v_add3_u32 v240, v233, v240, s60
	v_bfe_u32 v241, v232, 16, 1
	v_add3_u32 v241, v232, v241, s60
	v_lshrrev_b32_e32 v241, 16, v241
	v_and_or_b32 v50, v240, s33, v241
	v_bfe_u32 v240, v235, 16, 1
	v_add3_u32 v240, v235, v240, s60
	v_bfe_u32 v241, v234, 16, 1
	v_add3_u32 v241, v234, v241, s60
	v_lshrrev_b32_e32 v241, 16, v241
	v_and_or_b32 v51, v240, s33, v241
	v_bfe_u32 v240, v239, 16, 1
	v_add3_u32 v240, v239, v240, s60
	v_bfe_u32 v241, v238, 16, 1
	v_add3_u32 v241, v238, v241, s60
	v_lshrrev_b32_e32 v241, 16, v241
	v_and_or_b32 v52, v240, s33, v241
	v_bfe_u32 v240, v237, 16, 1
	v_add3_u32 v240, v237, v240, s60
	v_bfe_u32 v241, v236, 16, 1
	v_add3_u32 v241, v236, v241, s60
	v_lshrrev_b32_e32 v241, 16, v241
	v_and_or_b32 v53, v240, s33, v241
	v_ashrrev_i32_e32 v47, 31, v46
	v_lshlrev_b64 v[46:47], 12, v[46:47]
	v_lshl_add_u64 v[46:47], v[42:43], 0, v[46:47]
	global_store_dwordx4 v[46:47], v[50:53], off
.LBB0_1468:
	s_or_b64 exec, exec, s[24:25]
	v_add_u32_e32 v46, 24, v44
	v_cmp_gt_i32_e32 vcc, s0, v46
	s_and_saveexec_b64 s[24:25], vcc
	s_cbranch_execz .LBB0_1470
	ds_read2_b32 v[232:233], v49 offset0:152 offset1:217
	ds_read2_b32 v[234:235], v48 offset0:26 offset1:91
	ds_read2_b32 v[236:237], v0 offset0:30 offset1:95
	ds_read2_b32 v[238:239], v48 offset0:156 offset1:221
	s_waitcnt lgkmcnt(0)
	v_bfe_u32 v240, v233, 16, 1
	v_add3_u32 v240, v233, v240, s60
	v_bfe_u32 v241, v232, 16, 1
	v_add3_u32 v241, v232, v241, s60
	v_lshrrev_b32_e32 v241, 16, v241
	v_and_or_b32 v50, v240, s33, v241
	v_bfe_u32 v240, v235, 16, 1
	v_add3_u32 v240, v235, v240, s60
	v_bfe_u32 v241, v234, 16, 1
	v_add3_u32 v241, v234, v241, s60
	v_lshrrev_b32_e32 v241, 16, v241
	v_and_or_b32 v51, v240, s33, v241
	v_bfe_u32 v240, v239, 16, 1
	v_add3_u32 v240, v239, v240, s60
	v_bfe_u32 v241, v238, 16, 1
	v_add3_u32 v241, v238, v241, s60
	v_lshrrev_b32_e32 v241, 16, v241
	v_and_or_b32 v52, v240, s33, v241
	v_bfe_u32 v240, v237, 16, 1
	v_add3_u32 v240, v237, v240, s60
	v_bfe_u32 v241, v236, 16, 1
	v_add3_u32 v241, v236, v241, s60
	v_lshrrev_b32_e32 v241, 16, v241
	v_and_or_b32 v53, v240, s33, v241
	v_ashrrev_i32_e32 v47, 31, v46
	v_lshlrev_b64 v[46:47], 12, v[46:47]
	v_lshl_add_u64 v[46:47], v[42:43], 0, v[46:47]
	global_store_dwordx4 v[46:47], v[50:53], off
.LBB0_1470:
	s_or_b64 exec, exec, s[24:25]
	v_add_u32_e32 v46, 32, v44
	v_cmp_gt_i32_e32 vcc, s0, v46
	s_and_saveexec_b64 s[24:25], vcc
	s_cbranch_execz .LBB0_1472
	ds_read2_b32 v[232:233], v49 offset0:160 offset1:225
	ds_read2_b32 v[234:235], v48 offset0:34 offset1:99
	ds_read2_b32 v[236:237], v0 offset0:38 offset1:103
	ds_read2_b32 v[238:239], v48 offset0:164 offset1:229
	s_waitcnt lgkmcnt(0)
	v_bfe_u32 v240, v233, 16, 1
	v_add3_u32 v240, v233, v240, s60
	v_bfe_u32 v241, v232, 16, 1
	v_add3_u32 v241, v232, v241, s60
	v_lshrrev_b32_e32 v241, 16, v241
	v_and_or_b32 v50, v240, s33, v241
	v_bfe_u32 v240, v235, 16, 1
	v_add3_u32 v240, v235, v240, s60
	v_bfe_u32 v241, v234, 16, 1
	v_add3_u32 v241, v234, v241, s60
	v_lshrrev_b32_e32 v241, 16, v241
	v_and_or_b32 v51, v240, s33, v241
	v_bfe_u32 v240, v239, 16, 1
	v_add3_u32 v240, v239, v240, s60
	v_bfe_u32 v241, v238, 16, 1
	v_add3_u32 v241, v238, v241, s60
	v_lshrrev_b32_e32 v241, 16, v241
	v_and_or_b32 v52, v240, s33, v241
	v_bfe_u32 v240, v237, 16, 1
	v_add3_u32 v240, v237, v240, s60
	v_bfe_u32 v241, v236, 16, 1
	v_add3_u32 v241, v236, v241, s60
	v_lshrrev_b32_e32 v241, 16, v241
	v_and_or_b32 v53, v240, s33, v241
	v_ashrrev_i32_e32 v47, 31, v46
	v_lshlrev_b64 v[46:47], 12, v[46:47]
	v_lshl_add_u64 v[46:47], v[42:43], 0, v[46:47]
	global_store_dwordx4 v[46:47], v[50:53], off
.LBB0_1472:
	s_or_b64 exec, exec, s[24:25]
	v_add_u32_e32 v46, 40, v44
	v_cmp_gt_i32_e32 vcc, s0, v46
	s_and_saveexec_b64 s[24:25], vcc
	s_cbranch_execz .LBB0_1474
	ds_read2_b32 v[232:233], v49 offset0:168 offset1:233
	ds_read2_b32 v[234:235], v48 offset0:42 offset1:107
	ds_read2_b32 v[236:237], v0 offset0:46 offset1:111
	ds_read2_b32 v[238:239], v48 offset0:172 offset1:237
	s_waitcnt lgkmcnt(0)
	v_bfe_u32 v240, v233, 16, 1
	v_add3_u32 v240, v233, v240, s60
	v_bfe_u32 v241, v232, 16, 1
	v_add3_u32 v241, v232, v241, s60
	v_lshrrev_b32_e32 v241, 16, v241
	v_and_or_b32 v50, v240, s33, v241
	v_bfe_u32 v240, v235, 16, 1
	v_add3_u32 v240, v235, v240, s60
	v_bfe_u32 v241, v234, 16, 1
	v_add3_u32 v241, v234, v241, s60
	v_lshrrev_b32_e32 v241, 16, v241
	v_and_or_b32 v51, v240, s33, v241
	v_bfe_u32 v240, v239, 16, 1
	v_add3_u32 v240, v239, v240, s60
	v_bfe_u32 v241, v238, 16, 1
	v_add3_u32 v241, v238, v241, s60
	v_lshrrev_b32_e32 v241, 16, v241
	v_and_or_b32 v52, v240, s33, v241
	v_bfe_u32 v240, v237, 16, 1
	v_add3_u32 v240, v237, v240, s60
	v_bfe_u32 v241, v236, 16, 1
	v_add3_u32 v241, v236, v241, s60
	v_lshrrev_b32_e32 v241, 16, v241
	v_and_or_b32 v53, v240, s33, v241
	v_ashrrev_i32_e32 v47, 31, v46
	v_lshlrev_b64 v[46:47], 12, v[46:47]
	v_lshl_add_u64 v[46:47], v[42:43], 0, v[46:47]
	global_store_dwordx4 v[46:47], v[50:53], off
.LBB0_1474:
	s_or_b64 exec, exec, s[24:25]
	v_add_u32_e32 v46, 48, v44
	v_cmp_gt_i32_e32 vcc, s0, v46
	s_and_saveexec_b64 s[24:25], vcc
	s_cbranch_execz .LBB0_1476
	ds_read2_b32 v[232:233], v49 offset0:176 offset1:241
	ds_read2_b32 v[234:235], v48 offset0:50 offset1:115
	ds_read2_b32 v[236:237], v0 offset0:54 offset1:119
	ds_read2_b32 v[238:239], v48 offset0:180 offset1:245
	s_waitcnt lgkmcnt(0)
	v_bfe_u32 v240, v233, 16, 1
	v_add3_u32 v240, v233, v240, s60
	v_bfe_u32 v241, v232, 16, 1
	v_add3_u32 v241, v232, v241, s60
	v_lshrrev_b32_e32 v241, 16, v241
	v_and_or_b32 v50, v240, s33, v241
	v_bfe_u32 v240, v235, 16, 1
	v_add3_u32 v240, v235, v240, s60
	v_bfe_u32 v241, v234, 16, 1
	v_add3_u32 v241, v234, v241, s60
	v_lshrrev_b32_e32 v241, 16, v241
	v_and_or_b32 v51, v240, s33, v241
	v_bfe_u32 v240, v239, 16, 1
	v_add3_u32 v240, v239, v240, s60
	v_bfe_u32 v241, v238, 16, 1
	v_add3_u32 v241, v238, v241, s60
	v_lshrrev_b32_e32 v241, 16, v241
	v_and_or_b32 v52, v240, s33, v241
	v_bfe_u32 v240, v237, 16, 1
	v_add3_u32 v240, v237, v240, s60
	v_bfe_u32 v241, v236, 16, 1
	v_add3_u32 v241, v236, v241, s60
	v_lshrrev_b32_e32 v241, 16, v241
	v_and_or_b32 v53, v240, s33, v241
	v_ashrrev_i32_e32 v47, 31, v46
	v_lshlrev_b64 v[46:47], 12, v[46:47]
	v_lshl_add_u64 v[46:47], v[42:43], 0, v[46:47]
	global_store_dwordx4 v[46:47], v[50:53], off
.LBB0_1476:
	s_or_b64 exec, exec, s[24:25]
	v_add_u32_e32 v44, 56, v44
	v_cmp_gt_i32_e32 vcc, s0, v44
	s_and_saveexec_b64 s[24:25], vcc
	s_cbranch_execz .LBB0_1478
	ds_read2_b32 v[232:233], v49 offset0:184 offset1:249
	ds_read2_b32 v[234:235], v48 offset0:58 offset1:123
	ds_read2_b32 v[236:237], v48 offset0:188 offset1:253
	ds_read2_b32 v[238:239], v0 offset0:62 offset1:127
	s_waitcnt lgkmcnt(0)
	v_bfe_u32 v240, v233, 16, 1
	v_add3_u32 v240, v233, v240, s60
	v_bfe_u32 v241, v232, 16, 1
	v_add3_u32 v241, v232, v241, s60
	v_lshrrev_b32_e32 v241, 16, v241
	v_and_or_b32 v46, v240, s33, v241
	v_bfe_u32 v240, v235, 16, 1
	v_add3_u32 v240, v235, v240, s60
	v_bfe_u32 v241, v234, 16, 1
	v_add3_u32 v241, v234, v241, s60
	v_lshrrev_b32_e32 v241, 16, v241
	v_and_or_b32 v47, v240, s33, v241
	v_bfe_u32 v240, v237, 16, 1
	v_add3_u32 v240, v237, v240, s60
	v_bfe_u32 v241, v236, 16, 1
	v_add3_u32 v241, v236, v241, s60
	v_lshrrev_b32_e32 v241, 16, v241
	v_and_or_b32 v48, v240, s33, v241
	v_bfe_u32 v240, v239, 16, 1
	v_add3_u32 v240, v239, v240, s60
	v_bfe_u32 v241, v238, 16, 1
	v_add3_u32 v241, v238, v241, s60
	v_lshrrev_b32_e32 v241, 16, v241
	v_and_or_b32 v49, v240, s33, v241
	v_ashrrev_i32_e32 v45, 31, v44
	v_lshlrev_b64 v[44:45], 12, v[44:45]
	v_lshl_add_u64 v[42:43], v[42:43], 0, v[44:45]
	global_store_dwordx4 v[42:43], v[46:49], off

.LBB0_1513:
	s_or_b64 exec, exec, s[30:31]
	s_movk_i32 s1, 0x104
	v_mul_lo_u32 v116, v148, s1
	v_readlane_b32 s2, v251, 59
	s_lshl_b32 s0, s0, 1
	s_nop 0
	v_add3_u32 v0, s2, v0, v116
	v_add_u32_e32 v116, 0x2e00, v0
	s_waitcnt vmcnt(0)
	ds_write2_b32 v116, v42, v43 offset1:1
	v_add_u32_e32 v42, 0x2e08, v0
	ds_write2_b32 v42, v44, v45 offset1:1
	v_add_u32_e32 v42, 0x3210, v0
	ds_write2_b32 v42, v46, v47 offset1:1
	v_add_u32_e32 v42, 0x3218, v0
	ds_write2_b32 v42, v48, v49 offset1:1
	v_add_u32_e32 v42, 0x3620, v0
	ds_write2_b32 v42, v54, v55 offset1:1
	v_add_u32_e32 v42, 0x3628, v0
	ds_write2_b32 v42, v56, v57 offset1:1
	v_add_u32_e32 v42, 0x3a30, v0
	ds_write2_b32 v42, v50, v51 offset1:1
	v_add_u32_e32 v42, 0x3a38, v0
	ds_write2_b32 v42, v52, v53 offset1:1
	v_add_u32_e32 v42, 0x3e40, v0
	ds_write2_b32 v42, v62, v63 offset1:1
	v_add_u32_e32 v42, 0x3e48, v0
	ds_write2_b32 v42, v64, v65 offset1:1
	v_add_u32_e32 v42, 0x4250, v0
	ds_write2_b32 v42, v58, v59 offset1:1
	v_add_u32_e32 v42, 0x4258, v0
	ds_write2_b32 v42, v60, v61 offset1:1
	v_add_u32_e32 v42, 0x4660, v0
	ds_write2_b32 v42, v70, v71 offset1:1
	v_add_u32_e32 v42, 0x4668, v0
	ds_write2_b32 v42, v72, v73 offset1:1
	v_add_u32_e32 v42, 0x4a70, v0
	ds_write2_b32 v42, v66, v67 offset1:1
	v_add_u32_e32 v42, 0x4a78, v0
	ds_write2_b32 v42, v68, v69 offset1:1
	v_add_u32_e32 v42, 0x4e80, v0
	ds_write2_b32 v42, v78, v79 offset1:1
	v_add_u32_e32 v42, 0x4e88, v0
	ds_write2_b32 v42, v80, v81 offset1:1
	v_add_u32_e32 v42, 0x5290, v0
	ds_write2_b32 v42, v74, v75 offset1:1
	v_add_u32_e32 v42, 0x5298, v0
	ds_write2_b32 v42, v76, v77 offset1:1
	v_add_u32_e32 v42, 0x56a0, v0
	ds_write2_b32 v42, v86, v87 offset1:1
	v_add_u32_e32 v42, 0x56a8, v0
	ds_write2_b32 v42, v88, v89 offset1:1
	v_add_u32_e32 v42, 0x5ab0, v0
	ds_write2_b32 v42, v82, v83 offset1:1
	v_add_u32_e32 v42, 0x5ab8, v0
	ds_write2_b32 v42, v84, v85 offset1:1
	v_add_u32_e32 v42, 0x5ec0, v0
	ds_write2_b32 v42, v94, v95 offset1:1
	v_add_u32_e32 v42, 0x5ec8, v0
	ds_write2_b32 v42, v96, v97 offset1:1
	v_add_u32_e32 v42, 0x62d0, v0
	ds_write2_b32 v42, v90, v91 offset1:1
	v_add_u32_e32 v42, 0x62d8, v0
	ds_write2_b32 v42, v92, v93 offset1:1
	v_add_u32_e32 v42, 0x66e0, v0
	ds_write2_b32 v42, v102, v103 offset1:1
	v_add_u32_e32 v42, 0x66e8, v0
	ds_write2_b32 v42, v104, v105 offset1:1
	v_add_u32_e32 v42, 0x6af0, v0
	v_add_u32_e32 v0, 0x6af8, v0
	ds_write2_b32 v0, v100, v101 offset1:1
	v_lshlrev_b32_e32 v0, 3, v115
	ds_write2_b32 v42, v98, v99 offset1:1
	v_and_b32_e32 v0, 56, v0
	v_mov_b32_e32 v42, s2
	v_mad_u32_u24 v46, v0, s1, v42
	v_readlane_b32 s1, v250, 14
	s_add_u32 s0, s1, s0
	v_readlane_b32 s1, v250, 22
	s_waitcnt lgkmcnt(0)
	v_ashrrev_i32_e32 v45, 3, v115
	s_addc_u32 s1, s1, 0
	v_lshlrev_b32_e32 v0, 1, v0
	v_lshl_add_u64 v[42:43], s[0:1], 0, v[0:1]
	v_add_u32_e32 v44, s24, v45
	s_movk_i32 s0, 0x200
	v_lshl_add_u32 v0, v45, 2, v46
	v_cmp_gt_i32_e32 vcc, s0, v44
	v_add_u32_e32 v49, 0x2c00, v0
	v_add_u32_e32 v48, 0x3000, v0
	v_add_u32_e32 v0, 0x3400, v0
	s_and_saveexec_b64 s[2:3], vcc
	s_cbranch_execz .LBB0_1515
	ds_read2_b32 v[232:233], v49 offset0:128 offset1:193
	ds_read2_b32 v[234:235], v48 offset0:2 offset1:67
	ds_read2_b32 v[236:237], v0 offset0:6 offset1:71
	ds_read2_b32 v[238:239], v48 offset0:132 offset1:197
	s_waitcnt lgkmcnt(0)
	v_bfe_u32 v240, v233, 16, 1
	v_add3_u32 v240, v233, v240, s60
	v_bfe_u32 v241, v232, 16, 1
	v_add3_u32 v241, v232, v241, s60
	v_lshrrev_b32_e32 v241, 16, v241
	v_and_or_b32 v50, v240, s33, v241
	v_bfe_u32 v240, v235, 16, 1
	v_add3_u32 v240, v235, v240, s60
	v_bfe_u32 v241, v234, 16, 1
	v_add3_u32 v241, v234, v241, s60
	v_lshrrev_b32_e32 v241, 16, v241
	v_and_or_b32 v51, v240, s33, v241
	v_bfe_u32 v240, v239, 16, 1
	v_add3_u32 v240, v239, v240, s60
	v_bfe_u32 v241, v238, 16, 1
	v_add3_u32 v241, v238, v241, s60
	v_lshrrev_b32_e32 v241, 16, v241
	v_and_or_b32 v52, v240, s33, v241
	v_bfe_u32 v240, v237, 16, 1
	v_add3_u32 v240, v237, v240, s60
	v_bfe_u32 v241, v236, 16, 1
	v_add3_u32 v241, v236, v241, s60
	v_lshrrev_b32_e32 v241, 16, v241
	v_and_or_b32 v53, v240, s33, v241
	v_ashrrev_i32_e32 v45, 31, v44
	v_lshlrev_b64 v[46:47], 12, v[44:45]
	v_lshl_add_u64 v[46:47], v[42:43], 0, v[46:47]
	global_store_dwordx4 v[46:47], v[50:53], off
.LBB0_1515:
	s_or_b64 exec, exec, s[2:3]
	v_add_u32_e32 v46, 8, v44
	v_cmp_gt_i32_e32 vcc, s0, v46
	s_and_saveexec_b64 s[2:3], vcc
	s_cbranch_execz .LBB0_1517
	ds_read2_b32 v[232:233], v49 offset0:136 offset1:201
	ds_read2_b32 v[234:235], v48 offset0:10 offset1:75
	ds_read2_b32 v[236:237], v0 offset0:14 offset1:79
	ds_read2_b32 v[238:239], v48 offset0:140 offset1:205
	s_waitcnt lgkmcnt(0)
	v_bfe_u32 v240, v233, 16, 1
	v_add3_u32 v240, v233, v240, s60
	v_bfe_u32 v241, v232, 16, 1
	v_add3_u32 v241, v232, v241, s60
	v_lshrrev_b32_e32 v241, 16, v241
	v_and_or_b32 v50, v240, s33, v241
	v_bfe_u32 v240, v235, 16, 1
	v_add3_u32 v240, v235, v240, s60
	v_bfe_u32 v241, v234, 16, 1
	v_add3_u32 v241, v234, v241, s60
	v_lshrrev_b32_e32 v241, 16, v241
	v_and_or_b32 v51, v240, s33, v241
	v_bfe_u32 v240, v239, 16, 1
	v_add3_u32 v240, v239, v240, s60
	v_bfe_u32 v241, v238, 16, 1
	v_add3_u32 v241, v238, v241, s60
	v_lshrrev_b32_e32 v241, 16, v241
	v_and_or_b32 v52, v240, s33, v241
	v_bfe_u32 v240, v237, 16, 1
	v_add3_u32 v240, v237, v240, s60
	v_bfe_u32 v241, v236, 16, 1
	v_add3_u32 v241, v236, v241, s60
	v_lshrrev_b32_e32 v241, 16, v241
	v_and_or_b32 v53, v240, s33, v241
	v_ashrrev_i32_e32 v47, 31, v46
	v_lshlrev_b64 v[46:47], 12, v[46:47]
	v_lshl_add_u64 v[46:47], v[42:43], 0, v[46:47]
	global_store_dwordx4 v[46:47], v[50:53], off
.LBB0_1517:
	s_or_b64 exec, exec, s[2:3]
	v_add_u32_e32 v46, 16, v44
	v_cmp_gt_i32_e32 vcc, s0, v46
	s_and_saveexec_b64 s[2:3], vcc
	s_cbranch_execz .LBB0_1519
	ds_read2_b32 v[232:233], v49 offset0:144 offset1:209
	ds_read2_b32 v[234:235], v48 offset0:18 offset1:83
	ds_read2_b32 v[236:237], v0 offset0:22 offset1:87
	ds_read2_b32 v[238:239], v48 offset0:148 offset1:213
	s_waitcnt lgkmcnt(0)
	v_bfe_u32 v240, v233, 16, 1
	v_add3_u32 v240, v233, v240, s60
	v_bfe_u32 v241, v232, 16, 1
	v_add3_u32 v241, v232, v241, s60
	v_lshrrev_b32_e32 v241, 16, v241
	v_and_or_b32 v50, v240, s33, v241
	v_bfe_u32 v240, v235, 16, 1
	v_add3_u32 v240, v235, v240, s60
	v_bfe_u32 v241, v234, 16, 1
	v_add3_u32 v241, v234, v241, s60
	v_lshrrev_b32_e32 v241, 16, v241
	v_and_or_b32 v51, v240, s33, v241
	v_bfe_u32 v240, v239, 16, 1
	v_add3_u32 v240, v239, v240, s60
	v_bfe_u32 v241, v238, 16, 1
	v_add3_u32 v241, v238, v241, s60
	v_lshrrev_b32_e32 v241, 16, v241
	v_and_or_b32 v52, v240, s33, v241
	v_bfe_u32 v240, v237, 16, 1
	v_add3_u32 v240, v237, v240, s60
	v_bfe_u32 v241, v236, 16, 1
	v_add3_u32 v241, v236, v241, s60
	v_lshrrev_b32_e32 v241, 16, v241
	v_and_or_b32 v53, v240, s33, v241
	v_ashrrev_i32_e32 v47, 31, v46
	v_lshlrev_b64 v[46:47], 12, v[46:47]
	v_lshl_add_u64 v[46:47], v[42:43], 0, v[46:47]
	global_store_dwordx4 v[46:47], v[50:53], off
.LBB0_1519:
	s_or_b64 exec, exec, s[2:3]
	v_add_u32_e32 v46, 24, v44
	v_cmp_gt_i32_e32 vcc, s0, v46
	s_and_saveexec_b64 s[2:3], vcc
	s_cbranch_execz .LBB0_1521
	ds_read2_b32 v[232:233], v49 offset0:152 offset1:217
	ds_read2_b32 v[234:235], v48 offset0:26 offset1:91
	ds_read2_b32 v[236:237], v0 offset0:30 offset1:95
	ds_read2_b32 v[238:239], v48 offset0:156 offset1:221
	s_waitcnt lgkmcnt(0)
	v_bfe_u32 v240, v233, 16, 1
	v_add3_u32 v240, v233, v240, s60
	v_bfe_u32 v241, v232, 16, 1
	v_add3_u32 v241, v232, v241, s60
	v_lshrrev_b32_e32 v241, 16, v241
	v_and_or_b32 v50, v240, s33, v241
	v_bfe_u32 v240, v235, 16, 1
	v_add3_u32 v240, v235, v240, s60
	v_bfe_u32 v241, v234, 16, 1
	v_add3_u32 v241, v234, v241, s60
	v_lshrrev_b32_e32 v241, 16, v241
	v_and_or_b32 v51, v240, s33, v241
	v_bfe_u32 v240, v239, 16, 1
	v_add3_u32 v240, v239, v240, s60
	v_bfe_u32 v241, v238, 16, 1
	v_add3_u32 v241, v238, v241, s60
	v_lshrrev_b32_e32 v241, 16, v241
	v_and_or_b32 v52, v240, s33, v241
	v_bfe_u32 v240, v237, 16, 1
	v_add3_u32 v240, v237, v240, s60
	v_bfe_u32 v241, v236, 16, 1
	v_add3_u32 v241, v236, v241, s60
	v_lshrrev_b32_e32 v241, 16, v241
	v_and_or_b32 v53, v240, s33, v241
	v_ashrrev_i32_e32 v47, 31, v46
	v_lshlrev_b64 v[46:47], 12, v[46:47]
	v_lshl_add_u64 v[46:47], v[42:43], 0, v[46:47]
	global_store_dwordx4 v[46:47], v[50:53], off
.LBB0_1521:
	s_or_b64 exec, exec, s[2:3]
	v_add_u32_e32 v46, 32, v44
	v_cmp_gt_i32_e32 vcc, s0, v46
	s_and_saveexec_b64 s[2:3], vcc
	s_cbranch_execz .LBB0_1523
	ds_read2_b32 v[232:233], v49 offset0:160 offset1:225
	ds_read2_b32 v[234:235], v48 offset0:34 offset1:99
	ds_read2_b32 v[236:237], v0 offset0:38 offset1:103
	ds_read2_b32 v[238:239], v48 offset0:164 offset1:229
	s_waitcnt lgkmcnt(0)
	v_bfe_u32 v240, v233, 16, 1
	v_add3_u32 v240, v233, v240, s60
	v_bfe_u32 v241, v232, 16, 1
	v_add3_u32 v241, v232, v241, s60
	v_lshrrev_b32_e32 v241, 16, v241
	v_and_or_b32 v50, v240, s33, v241
	v_bfe_u32 v240, v235, 16, 1
	v_add3_u32 v240, v235, v240, s60
	v_bfe_u32 v241, v234, 16, 1
	v_add3_u32 v241, v234, v241, s60
	v_lshrrev_b32_e32 v241, 16, v241
	v_and_or_b32 v51, v240, s33, v241
	v_bfe_u32 v240, v239, 16, 1
	v_add3_u32 v240, v239, v240, s60
	v_bfe_u32 v241, v238, 16, 1
	v_add3_u32 v241, v238, v241, s60
	v_lshrrev_b32_e32 v241, 16, v241
	v_and_or_b32 v52, v240, s33, v241
	v_bfe_u32 v240, v237, 16, 1
	v_add3_u32 v240, v237, v240, s60
	v_bfe_u32 v241, v236, 16, 1
	v_add3_u32 v241, v236, v241, s60
	v_lshrrev_b32_e32 v241, 16, v241
	v_and_or_b32 v53, v240, s33, v241
	v_ashrrev_i32_e32 v47, 31, v46
	v_lshlrev_b64 v[46:47], 12, v[46:47]
	v_lshl_add_u64 v[46:47], v[42:43], 0, v[46:47]
	global_store_dwordx4 v[46:47], v[50:53], off
.LBB0_1523:
	s_or_b64 exec, exec, s[2:3]
	v_add_u32_e32 v46, 40, v44
	v_cmp_gt_i32_e32 vcc, s0, v46
	s_and_saveexec_b64 s[2:3], vcc
	s_cbranch_execz .LBB0_1525
	ds_read2_b32 v[232:233], v49 offset0:168 offset1:233
	ds_read2_b32 v[234:235], v48 offset0:42 offset1:107
	ds_read2_b32 v[236:237], v0 offset0:46 offset1:111
	ds_read2_b32 v[238:239], v48 offset0:172 offset1:237
	s_waitcnt lgkmcnt(0)
	v_bfe_u32 v240, v233, 16, 1
	v_add3_u32 v240, v233, v240, s60
	v_bfe_u32 v241, v232, 16, 1
	v_add3_u32 v241, v232, v241, s60
	v_lshrrev_b32_e32 v241, 16, v241
	v_and_or_b32 v50, v240, s33, v241
	v_bfe_u32 v240, v235, 16, 1
	v_add3_u32 v240, v235, v240, s60
	v_bfe_u32 v241, v234, 16, 1
	v_add3_u32 v241, v234, v241, s60
	v_lshrrev_b32_e32 v241, 16, v241
	v_and_or_b32 v51, v240, s33, v241
	v_bfe_u32 v240, v239, 16, 1
	v_add3_u32 v240, v239, v240, s60
	v_bfe_u32 v241, v238, 16, 1
	v_add3_u32 v241, v238, v241, s60
	v_lshrrev_b32_e32 v241, 16, v241
	v_and_or_b32 v52, v240, s33, v241
	v_bfe_u32 v240, v237, 16, 1
	v_add3_u32 v240, v237, v240, s60
	v_bfe_u32 v241, v236, 16, 1
	v_add3_u32 v241, v236, v241, s60
	v_lshrrev_b32_e32 v241, 16, v241
	v_and_or_b32 v53, v240, s33, v241
	v_ashrrev_i32_e32 v47, 31, v46
	v_lshlrev_b64 v[46:47], 12, v[46:47]
	v_lshl_add_u64 v[46:47], v[42:43], 0, v[46:47]
	global_store_dwordx4 v[46:47], v[50:53], off
.LBB0_1525:
	s_or_b64 exec, exec, s[2:3]
	v_add_u32_e32 v46, 48, v44
	v_cmp_gt_i32_e32 vcc, s0, v46
	s_and_saveexec_b64 s[2:3], vcc
	s_cbranch_execz .LBB0_1527
	ds_read2_b32 v[232:233], v49 offset0:176 offset1:241
	ds_read2_b32 v[234:235], v48 offset0:50 offset1:115
	ds_read2_b32 v[236:237], v0 offset0:54 offset1:119
	ds_read2_b32 v[238:239], v48 offset0:180 offset1:245
	s_waitcnt lgkmcnt(0)
	v_bfe_u32 v240, v233, 16, 1
	v_add3_u32 v240, v233, v240, s60
	v_bfe_u32 v241, v232, 16, 1
	v_add3_u32 v241, v232, v241, s60
	v_lshrrev_b32_e32 v241, 16, v241
	v_and_or_b32 v50, v240, s33, v241
	v_bfe_u32 v240, v235, 16, 1
	v_add3_u32 v240, v235, v240, s60
	v_bfe_u32 v241, v234, 16, 1
	v_add3_u32 v241, v234, v241, s60
	v_lshrrev_b32_e32 v241, 16, v241
	v_and_or_b32 v51, v240, s33, v241
	v_bfe_u32 v240, v239, 16, 1
	v_add3_u32 v240, v239, v240, s60
	v_bfe_u32 v241, v238, 16, 1
	v_add3_u32 v241, v238, v241, s60
	v_lshrrev_b32_e32 v241, 16, v241
	v_and_or_b32 v52, v240, s33, v241
	v_bfe_u32 v240, v237, 16, 1
	v_add3_u32 v240, v237, v240, s60
	v_bfe_u32 v241, v236, 16, 1
	v_add3_u32 v241, v236, v241, s60
	v_lshrrev_b32_e32 v241, 16, v241
	v_and_or_b32 v53, v240, s33, v241
	v_ashrrev_i32_e32 v47, 31, v46
	v_lshlrev_b64 v[46:47], 12, v[46:47]
	v_lshl_add_u64 v[46:47], v[42:43], 0, v[46:47]
	global_store_dwordx4 v[46:47], v[50:53], off
.LBB0_1527:
	s_or_b64 exec, exec, s[2:3]
	v_add_u32_e32 v44, 56, v44
	v_cmp_gt_i32_e32 vcc, s0, v44
	s_and_saveexec_b64 s[2:3], vcc
	s_cbranch_execz .LBB0_1529
	ds_read2_b32 v[232:233], v49 offset0:184 offset1:249
	ds_read2_b32 v[234:235], v48 offset0:58 offset1:123
	ds_read2_b32 v[236:237], v48 offset0:188 offset1:253
	ds_read2_b32 v[238:239], v0 offset0:62 offset1:127
	s_waitcnt lgkmcnt(0)
	v_bfe_u32 v240, v233, 16, 1
	v_add3_u32 v240, v233, v240, s60
	v_bfe_u32 v241, v232, 16, 1
	v_add3_u32 v241, v232, v241, s60
	v_lshrrev_b32_e32 v241, 16, v241
	v_and_or_b32 v46, v240, s33, v241
	v_bfe_u32 v240, v235, 16, 1
	v_add3_u32 v240, v235, v240, s60
	v_bfe_u32 v241, v234, 16, 1
	v_add3_u32 v241, v234, v241, s60
	v_lshrrev_b32_e32 v241, 16, v241
	v_and_or_b32 v47, v240, s33, v241
	v_bfe_u32 v240, v237, 16, 1
	v_add3_u32 v240, v237, v240, s60
	v_bfe_u32 v241, v236, 16, 1
	v_add3_u32 v241, v236, v241, s60
	v_lshrrev_b32_e32 v241, 16, v241
	v_and_or_b32 v48, v240, s33, v241
	v_bfe_u32 v240, v239, 16, 1
	v_add3_u32 v240, v239, v240, s60
	v_bfe_u32 v241, v238, 16, 1
	v_add3_u32 v241, v238, v241, s60
	v_lshrrev_b32_e32 v241, 16, v241
	v_and_or_b32 v49, v240, s33, v241
	v_ashrrev_i32_e32 v45, 31, v44
	v_lshlrev_b64 v[44:45], 12, v[44:45]
	v_lshl_add_u64 v[42:43], v[42:43], 0, v[44:45]
	global_store_dwordx4 v[42:43], v[46:49], off

.LBB0_1564:
	s_or_b64 exec, exec, s[30:31]
	s_movk_i32 s1, 0x104
	v_mul_lo_u32 v116, v148, s1
	v_readlane_b32 s2, v251, 59
	s_lshl_b32 s0, s0, 1
	s_nop 0
	v_add3_u32 v0, s2, v0, v116
	v_add_u32_e32 v116, 0x2e00, v0
	s_waitcnt vmcnt(0)
	ds_write2_b32 v116, v42, v43 offset1:1
	v_add_u32_e32 v42, 0x2e08, v0
	ds_write2_b32 v42, v44, v45 offset1:1
	v_add_u32_e32 v42, 0x3210, v0
	ds_write2_b32 v42, v46, v47 offset1:1
	v_add_u32_e32 v42, 0x3218, v0
	ds_write2_b32 v42, v48, v49 offset1:1
	v_add_u32_e32 v42, 0x3620, v0
	ds_write2_b32 v42, v54, v55 offset1:1
	v_add_u32_e32 v42, 0x3628, v0
	ds_write2_b32 v42, v56, v57 offset1:1
	v_add_u32_e32 v42, 0x3a30, v0
	ds_write2_b32 v42, v50, v51 offset1:1
	v_add_u32_e32 v42, 0x3a38, v0
	ds_write2_b32 v42, v52, v53 offset1:1
	v_add_u32_e32 v42, 0x3e40, v0
	ds_write2_b32 v42, v62, v63 offset1:1
	v_add_u32_e32 v42, 0x3e48, v0
	ds_write2_b32 v42, v64, v65 offset1:1
	v_add_u32_e32 v42, 0x4250, v0
	ds_write2_b32 v42, v58, v59 offset1:1
	v_add_u32_e32 v42, 0x4258, v0
	ds_write2_b32 v42, v60, v61 offset1:1
	v_add_u32_e32 v42, 0x4660, v0
	ds_write2_b32 v42, v70, v71 offset1:1
	v_add_u32_e32 v42, 0x4668, v0
	ds_write2_b32 v42, v72, v73 offset1:1
	v_add_u32_e32 v42, 0x4a70, v0
	ds_write2_b32 v42, v66, v67 offset1:1
	v_add_u32_e32 v42, 0x4a78, v0
	ds_write2_b32 v42, v68, v69 offset1:1
	v_add_u32_e32 v42, 0x4e80, v0
	ds_write2_b32 v42, v78, v79 offset1:1
	v_add_u32_e32 v42, 0x4e88, v0
	ds_write2_b32 v42, v80, v81 offset1:1
	v_add_u32_e32 v42, 0x5290, v0
	ds_write2_b32 v42, v74, v75 offset1:1
	v_add_u32_e32 v42, 0x5298, v0
	ds_write2_b32 v42, v76, v77 offset1:1
	v_add_u32_e32 v42, 0x56a0, v0
	ds_write2_b32 v42, v86, v87 offset1:1
	v_add_u32_e32 v42, 0x56a8, v0
	ds_write2_b32 v42, v88, v89 offset1:1
	v_add_u32_e32 v42, 0x5ab0, v0
	ds_write2_b32 v42, v82, v83 offset1:1
	v_add_u32_e32 v42, 0x5ab8, v0
	ds_write2_b32 v42, v84, v85 offset1:1
	v_add_u32_e32 v42, 0x5ec0, v0
	ds_write2_b32 v42, v94, v95 offset1:1
	v_add_u32_e32 v42, 0x5ec8, v0
	ds_write2_b32 v42, v96, v97 offset1:1
	v_add_u32_e32 v42, 0x62d0, v0
	ds_write2_b32 v42, v90, v91 offset1:1
	v_add_u32_e32 v42, 0x62d8, v0
	ds_write2_b32 v42, v92, v93 offset1:1
	v_add_u32_e32 v42, 0x66e0, v0
	ds_write2_b32 v42, v102, v103 offset1:1
	v_add_u32_e32 v42, 0x66e8, v0
	ds_write2_b32 v42, v104, v105 offset1:1
	v_add_u32_e32 v42, 0x6af0, v0
	v_add_u32_e32 v0, 0x6af8, v0
	ds_write2_b32 v0, v100, v101 offset1:1
	v_lshlrev_b32_e32 v0, 3, v115
	ds_write2_b32 v42, v98, v99 offset1:1
	v_and_b32_e32 v0, 56, v0
	v_mov_b32_e32 v42, s2
	v_mad_u32_u24 v46, v0, s1, v42
	v_readlane_b32 s1, v250, 38
	s_add_u32 s0, s1, s0
	v_readlane_b32 s1, v250, 10
	s_waitcnt lgkmcnt(0)
	v_ashrrev_i32_e32 v45, 3, v115
	s_addc_u32 s1, s1, 0
	v_lshlrev_b32_e32 v0, 1, v0
	v_lshl_add_u64 v[42:43], s[0:1], 0, v[0:1]
	v_add_u32_e32 v44, s24, v45
	s_movk_i32 s0, 0x800
	v_lshl_add_u32 v0, v45, 2, v46
	v_cmp_gt_i32_e32 vcc, s0, v44
	v_add_u32_e32 v49, 0x2c00, v0
	v_add_u32_e32 v48, 0x3000, v0
	v_add_u32_e32 v0, 0x3400, v0
	s_and_saveexec_b64 s[2:3], vcc
	s_cbranch_execz .LBB0_1566
	ds_read2_b32 v[232:233], v49 offset0:128 offset1:193
	ds_read2_b32 v[234:235], v48 offset0:2 offset1:67
	ds_read2_b32 v[236:237], v0 offset0:6 offset1:71
	ds_read2_b32 v[238:239], v48 offset0:132 offset1:197
	s_waitcnt lgkmcnt(0)
	v_bfe_u32 v240, v233, 16, 1
	v_add3_u32 v240, v233, v240, s60
	v_bfe_u32 v241, v232, 16, 1
	v_add3_u32 v241, v232, v241, s60
	v_lshrrev_b32_e32 v241, 16, v241
	v_and_or_b32 v50, v240, s33, v241
	v_bfe_u32 v240, v235, 16, 1
	v_add3_u32 v240, v235, v240, s60
	v_bfe_u32 v241, v234, 16, 1
	v_add3_u32 v241, v234, v241, s60
	v_lshrrev_b32_e32 v241, 16, v241
	v_and_or_b32 v51, v240, s33, v241
	v_bfe_u32 v240, v239, 16, 1
	v_add3_u32 v240, v239, v240, s60
	v_bfe_u32 v241, v238, 16, 1
	v_add3_u32 v241, v238, v241, s60
	v_lshrrev_b32_e32 v241, 16, v241
	v_and_or_b32 v52, v240, s33, v241
	v_bfe_u32 v240, v237, 16, 1
	v_add3_u32 v240, v237, v240, s60
	v_bfe_u32 v241, v236, 16, 1
	v_add3_u32 v241, v236, v241, s60
	v_lshrrev_b32_e32 v241, 16, v241
	v_and_or_b32 v53, v240, s33, v241
	v_ashrrev_i32_e32 v45, 31, v44
	v_lshlrev_b64 v[46:47], 12, v[44:45]
	v_lshl_add_u64 v[46:47], v[42:43], 0, v[46:47]
	global_store_dwordx4 v[46:47], v[50:53], off

.LBB0_1768:
	s_or_b64 exec, exec, s[30:31]
	s_movk_i32 s0, 0x104
	v_mul_lo_u32 v116, v118, s0
	v_readlane_b32 s1, v251, 59
	s_ashr_i32 s25, s24, 31
	v_readlane_b32 s3, v251, 61
	v_add3_u32 v0, s1, v0, v116
	v_add_u32_e32 v116, 0x2e00, v0
	s_waitcnt vmcnt(0)
	ds_write2_b32 v116, v46, v47 offset1:1
	v_add_u32_e32 v46, 0x2e08, v0
	ds_write2_b32 v46, v48, v49 offset1:1
	v_add_u32_e32 v46, 0x3210, v0
	ds_write2_b32 v46, v42, v43 offset1:1
	v_add_u32_e32 v42, 0x3218, v0
	ds_write2_b32 v42, v44, v45 offset1:1
	v_add_u32_e32 v42, 0x3620, v0
	ds_write2_b32 v42, v54, v55 offset1:1
	v_add_u32_e32 v42, 0x3628, v0
	ds_write2_b32 v42, v56, v57 offset1:1
	v_add_u32_e32 v42, 0x3a30, v0
	ds_write2_b32 v42, v50, v51 offset1:1
	v_add_u32_e32 v42, 0x3a38, v0
	ds_write2_b32 v42, v52, v53 offset1:1
	v_add_u32_e32 v42, 0x3e40, v0
	ds_write2_b32 v42, v62, v63 offset1:1
	v_add_u32_e32 v42, 0x3e48, v0
	ds_write2_b32 v42, v64, v65 offset1:1
	v_add_u32_e32 v42, 0x4250, v0
	ds_write2_b32 v42, v58, v59 offset1:1
	v_add_u32_e32 v42, 0x4258, v0
	ds_write2_b32 v42, v60, v61 offset1:1
	v_add_u32_e32 v42, 0x4660, v0
	ds_write2_b32 v42, v70, v71 offset1:1
	v_add_u32_e32 v42, 0x4668, v0
	ds_write2_b32 v42, v72, v73 offset1:1
	v_add_u32_e32 v42, 0x4a70, v0
	ds_write2_b32 v42, v66, v67 offset1:1
	v_add_u32_e32 v42, 0x4a78, v0
	ds_write2_b32 v42, v68, v69 offset1:1
	v_add_u32_e32 v42, 0x4e80, v0
	ds_write2_b32 v42, v78, v79 offset1:1
	v_add_u32_e32 v42, 0x4e88, v0
	ds_write2_b32 v42, v80, v81 offset1:1
	v_add_u32_e32 v42, 0x5290, v0
	ds_write2_b32 v42, v74, v75 offset1:1
	v_add_u32_e32 v42, 0x5298, v0
	ds_write2_b32 v42, v76, v77 offset1:1
	v_add_u32_e32 v42, 0x56a0, v0
	ds_write2_b32 v42, v86, v87 offset1:1
	v_add_u32_e32 v42, 0x56a8, v0
	ds_write2_b32 v42, v88, v89 offset1:1
	v_add_u32_e32 v42, 0x5ab0, v0
	ds_write2_b32 v42, v82, v83 offset1:1
	v_add_u32_e32 v42, 0x5ab8, v0
	ds_write2_b32 v42, v84, v85 offset1:1
	v_add_u32_e32 v42, 0x5ec0, v0
	ds_write2_b32 v42, v94, v95 offset1:1
	v_add_u32_e32 v42, 0x5ec8, v0
	ds_write2_b32 v42, v96, v97 offset1:1
	v_add_u32_e32 v42, 0x62d0, v0
	ds_write2_b32 v42, v90, v91 offset1:1
	v_add_u32_e32 v42, 0x62d8, v0
	ds_write2_b32 v42, v92, v93 offset1:1
	v_add_u32_e32 v42, 0x66e0, v0
	ds_write2_b32 v42, v102, v103 offset1:1
	v_add_u32_e32 v42, 0x66e8, v0
	ds_write2_b32 v42, v104, v105 offset1:1
	v_add_u32_e32 v42, 0x6af0, v0
	v_add_u32_e32 v0, 0x6af8, v0
	ds_write2_b32 v0, v100, v101 offset1:1
	v_lshlrev_b32_e32 v0, 3, v115
	ds_write2_b32 v42, v98, v99 offset1:1
	v_and_b32_e32 v0, 56, v0
	v_mov_b32_e32 v42, s1
	v_mad_u32_u24 v46, v0, s0, v42
	s_lshl_b64 s[0:1], s[24:25], 1
	s_add_u32 s0, s3, s0
	v_readlane_b32 s3, v251, 63
	s_waitcnt lgkmcnt(0)
	v_ashrrev_i32_e32 v45, 3, v115
	s_addc_u32 s1, s3, s1
	v_lshlrev_b32_e32 v0, 1, v0
	v_lshl_add_u64 v[42:43], s[0:1], 0, v[0:1]
	v_add_u32_e32 v44, s2, v45
	v_lshl_add_u32 v0, v45, 2, v46
	v_cmp_gt_i32_e32 vcc, s97, v44
	v_add_u32_e32 v49, 0x2c00, v0
	v_add_u32_e32 v48, 0x3000, v0
	v_add_u32_e32 v0, 0x3400, v0
	s_and_saveexec_b64 s[2:3], vcc
	s_cbranch_execz .LBB0_1770
	ds_read2_b32 v[232:233], v49 offset0:128 offset1:193
	ds_read2_b32 v[234:235], v48 offset0:2 offset1:67
	ds_read2_b32 v[236:237], v0 offset0:6 offset1:71
	ds_read2_b32 v[238:239], v48 offset0:132 offset1:197
	s_waitcnt lgkmcnt(0)
	v_bfe_u32 v240, v233, 16, 1
	v_add3_u32 v240, v233, v240, s60
	v_bfe_u32 v241, v232, 16, 1
	v_add3_u32 v241, v232, v241, s60
	v_lshrrev_b32_e32 v241, 16, v241
	v_and_or_b32 v50, v240, s33, v241
	v_bfe_u32 v240, v235, 16, 1
	v_add3_u32 v240, v235, v240, s60
	v_bfe_u32 v241, v234, 16, 1
	v_add3_u32 v241, v234, v241, s60
	v_lshrrev_b32_e32 v241, 16, v241
	v_and_or_b32 v51, v240, s33, v241
	v_bfe_u32 v240, v239, 16, 1
	v_add3_u32 v240, v239, v240, s60
	v_bfe_u32 v241, v238, 16, 1
	v_add3_u32 v241, v238, v241, s60
	v_lshrrev_b32_e32 v241, 16, v241
	v_and_or_b32 v52, v240, s33, v241
	v_bfe_u32 v240, v237, 16, 1
	v_add3_u32 v240, v237, v240, s60
	v_bfe_u32 v241, v236, 16, 1
	v_add3_u32 v241, v236, v241, s60
	v_lshrrev_b32_e32 v241, 16, v241
	v_and_or_b32 v53, v240, s33, v241
	v_ashrrev_i32_e32 v45, 31, v44
	v_lshlrev_b64 v[46:47], 12, v[44:45]
	v_lshl_add_u64 v[46:47], v[42:43], 0, v[46:47]
	global_store_dwordx4 v[46:47], v[50:53], off
.LBB0_1770:
	s_or_b64 exec, exec, s[2:3]
	v_add_u32_e32 v46, 8, v44
	v_cmp_gt_i32_e32 vcc, s97, v46
	s_and_saveexec_b64 s[2:3], vcc
	s_cbranch_execz .LBB0_1772
	ds_read2_b32 v[232:233], v49 offset0:136 offset1:201
	ds_read2_b32 v[234:235], v48 offset0:10 offset1:75
	ds_read2_b32 v[236:237], v0 offset0:14 offset1:79
	ds_read2_b32 v[238:239], v48 offset0:140 offset1:205
	s_waitcnt lgkmcnt(0)
	v_bfe_u32 v240, v233, 16, 1
	v_add3_u32 v240, v233, v240, s60
	v_bfe_u32 v241, v232, 16, 1
	v_add3_u32 v241, v232, v241, s60
	v_lshrrev_b32_e32 v241, 16, v241
	v_and_or_b32 v50, v240, s33, v241
	v_bfe_u32 v240, v235, 16, 1
	v_add3_u32 v240, v235, v240, s60
	v_bfe_u32 v241, v234, 16, 1
	v_add3_u32 v241, v234, v241, s60
	v_lshrrev_b32_e32 v241, 16, v241
	v_and_or_b32 v51, v240, s33, v241
	v_bfe_u32 v240, v239, 16, 1
	v_add3_u32 v240, v239, v240, s60
	v_bfe_u32 v241, v238, 16, 1
	v_add3_u32 v241, v238, v241, s60
	v_lshrrev_b32_e32 v241, 16, v241
	v_and_or_b32 v52, v240, s33, v241
	v_bfe_u32 v240, v237, 16, 1
	v_add3_u32 v240, v237, v240, s60
	v_bfe_u32 v241, v236, 16, 1
	v_add3_u32 v241, v236, v241, s60
	v_lshrrev_b32_e32 v241, 16, v241
	v_and_or_b32 v53, v240, s33, v241
	v_ashrrev_i32_e32 v47, 31, v46
	v_lshlrev_b64 v[46:47], 12, v[46:47]
	v_lshl_add_u64 v[46:47], v[42:43], 0, v[46:47]
	global_store_dwordx4 v[46:47], v[50:53], off
.LBB0_1772:
	s_or_b64 exec, exec, s[2:3]
	v_add_u32_e32 v46, 16, v44
	v_cmp_gt_i32_e32 vcc, s97, v46
	s_and_saveexec_b64 s[2:3], vcc
	s_cbranch_execz .LBB0_1774
	ds_read2_b32 v[232:233], v49 offset0:144 offset1:209
	ds_read2_b32 v[234:235], v48 offset0:18 offset1:83
	ds_read2_b32 v[236:237], v0 offset0:22 offset1:87
	ds_read2_b32 v[238:239], v48 offset0:148 offset1:213
	s_waitcnt lgkmcnt(0)
	v_bfe_u32 v240, v233, 16, 1
	v_add3_u32 v240, v233, v240, s60
	v_bfe_u32 v241, v232, 16, 1
	v_add3_u32 v241, v232, v241, s60
	v_lshrrev_b32_e32 v241, 16, v241
	v_and_or_b32 v50, v240, s33, v241
	v_bfe_u32 v240, v235, 16, 1
	v_add3_u32 v240, v235, v240, s60
	v_bfe_u32 v241, v234, 16, 1
	v_add3_u32 v241, v234, v241, s60
	v_lshrrev_b32_e32 v241, 16, v241
	v_and_or_b32 v51, v240, s33, v241
	v_bfe_u32 v240, v239, 16, 1
	v_add3_u32 v240, v239, v240, s60
	v_bfe_u32 v241, v238, 16, 1
	v_add3_u32 v241, v238, v241, s60
	v_lshrrev_b32_e32 v241, 16, v241
	v_and_or_b32 v52, v240, s33, v241
	v_bfe_u32 v240, v237, 16, 1
	v_add3_u32 v240, v237, v240, s60
	v_bfe_u32 v241, v236, 16, 1
	v_add3_u32 v241, v236, v241, s60
	v_lshrrev_b32_e32 v241, 16, v241
	v_and_or_b32 v53, v240, s33, v241
	v_ashrrev_i32_e32 v47, 31, v46
	v_lshlrev_b64 v[46:47], 12, v[46:47]
	v_lshl_add_u64 v[46:47], v[42:43], 0, v[46:47]
	global_store_dwordx4 v[46:47], v[50:53], off
.LBB0_1774:
	s_or_b64 exec, exec, s[2:3]
	v_add_u32_e32 v46, 24, v44
	v_cmp_gt_i32_e32 vcc, s97, v46
	s_and_saveexec_b64 s[2:3], vcc
	s_cbranch_execz .LBB0_1776
	ds_read2_b32 v[232:233], v49 offset0:152 offset1:217
	ds_read2_b32 v[234:235], v48 offset0:26 offset1:91
	ds_read2_b32 v[236:237], v0 offset0:30 offset1:95
	ds_read2_b32 v[238:239], v48 offset0:156 offset1:221
	s_waitcnt lgkmcnt(0)
	v_bfe_u32 v240, v233, 16, 1
	v_add3_u32 v240, v233, v240, s60
	v_bfe_u32 v241, v232, 16, 1
	v_add3_u32 v241, v232, v241, s60
	v_lshrrev_b32_e32 v241, 16, v241
	v_and_or_b32 v50, v240, s33, v241
	v_bfe_u32 v240, v235, 16, 1
	v_add3_u32 v240, v235, v240, s60
	v_bfe_u32 v241, v234, 16, 1
	v_add3_u32 v241, v234, v241, s60
	v_lshrrev_b32_e32 v241, 16, v241
	v_and_or_b32 v51, v240, s33, v241
	v_bfe_u32 v240, v239, 16, 1
	v_add3_u32 v240, v239, v240, s60
	v_bfe_u32 v241, v238, 16, 1
	v_add3_u32 v241, v238, v241, s60
	v_lshrrev_b32_e32 v241, 16, v241
	v_and_or_b32 v52, v240, s33, v241
	v_bfe_u32 v240, v237, 16, 1
	v_add3_u32 v240, v237, v240, s60
	v_bfe_u32 v241, v236, 16, 1
	v_add3_u32 v241, v236, v241, s60
	v_lshrrev_b32_e32 v241, 16, v241
	v_and_or_b32 v53, v240, s33, v241
	v_ashrrev_i32_e32 v47, 31, v46
	v_lshlrev_b64 v[46:47], 12, v[46:47]
	v_lshl_add_u64 v[46:47], v[42:43], 0, v[46:47]
	global_store_dwordx4 v[46:47], v[50:53], off
.LBB0_1776:
	s_or_b64 exec, exec, s[2:3]
	v_add_u32_e32 v46, 32, v44
	v_cmp_gt_i32_e32 vcc, s97, v46
	s_and_saveexec_b64 s[2:3], vcc
	s_cbranch_execz .LBB0_1778
	ds_read2_b32 v[232:233], v49 offset0:160 offset1:225
	ds_read2_b32 v[234:235], v48 offset0:34 offset1:99
	ds_read2_b32 v[236:237], v0 offset0:38 offset1:103
	ds_read2_b32 v[238:239], v48 offset0:164 offset1:229
	s_waitcnt lgkmcnt(0)
	v_bfe_u32 v240, v233, 16, 1
	v_add3_u32 v240, v233, v240, s60
	v_bfe_u32 v241, v232, 16, 1
	v_add3_u32 v241, v232, v241, s60
	v_lshrrev_b32_e32 v241, 16, v241
	v_and_or_b32 v50, v240, s33, v241
	v_bfe_u32 v240, v235, 16, 1
	v_add3_u32 v240, v235, v240, s60
	v_bfe_u32 v241, v234, 16, 1
	v_add3_u32 v241, v234, v241, s60
	v_lshrrev_b32_e32 v241, 16, v241
	v_and_or_b32 v51, v240, s33, v241
	v_bfe_u32 v240, v239, 16, 1
	v_add3_u32 v240, v239, v240, s60
	v_bfe_u32 v241, v238, 16, 1
	v_add3_u32 v241, v238, v241, s60
	v_lshrrev_b32_e32 v241, 16, v241
	v_and_or_b32 v52, v240, s33, v241
	v_bfe_u32 v240, v237, 16, 1
	v_add3_u32 v240, v237, v240, s60
	v_bfe_u32 v241, v236, 16, 1
	v_add3_u32 v241, v236, v241, s60
	v_lshrrev_b32_e32 v241, 16, v241
	v_and_or_b32 v53, v240, s33, v241
	v_ashrrev_i32_e32 v47, 31, v46
	v_lshlrev_b64 v[46:47], 12, v[46:47]
	v_lshl_add_u64 v[46:47], v[42:43], 0, v[46:47]
	global_store_dwordx4 v[46:47], v[50:53], off
.LBB0_1778:
	s_or_b64 exec, exec, s[2:3]
	v_add_u32_e32 v46, 40, v44
	v_cmp_gt_i32_e32 vcc, s97, v46
	s_and_saveexec_b64 s[2:3], vcc
	s_cbranch_execz .LBB0_1780
	ds_read2_b32 v[232:233], v49 offset0:168 offset1:233
	ds_read2_b32 v[234:235], v48 offset0:42 offset1:107
	ds_read2_b32 v[236:237], v0 offset0:46 offset1:111
	ds_read2_b32 v[238:239], v48 offset0:172 offset1:237
	s_waitcnt lgkmcnt(0)
	v_bfe_u32 v240, v233, 16, 1
	v_add3_u32 v240, v233, v240, s60
	v_bfe_u32 v241, v232, 16, 1
	v_add3_u32 v241, v232, v241, s60
	v_lshrrev_b32_e32 v241, 16, v241
	v_and_or_b32 v50, v240, s33, v241
	v_bfe_u32 v240, v235, 16, 1
	v_add3_u32 v240, v235, v240, s60
	v_bfe_u32 v241, v234, 16, 1
	v_add3_u32 v241, v234, v241, s60
	v_lshrrev_b32_e32 v241, 16, v241
	v_and_or_b32 v51, v240, s33, v241
	v_bfe_u32 v240, v239, 16, 1
	v_add3_u32 v240, v239, v240, s60
	v_bfe_u32 v241, v238, 16, 1
	v_add3_u32 v241, v238, v241, s60
	v_lshrrev_b32_e32 v241, 16, v241
	v_and_or_b32 v52, v240, s33, v241
	v_bfe_u32 v240, v237, 16, 1
	v_add3_u32 v240, v237, v240, s60
	v_bfe_u32 v241, v236, 16, 1
	v_add3_u32 v241, v236, v241, s60
	v_lshrrev_b32_e32 v241, 16, v241
	v_and_or_b32 v53, v240, s33, v241
	v_ashrrev_i32_e32 v47, 31, v46
	v_lshlrev_b64 v[46:47], 12, v[46:47]
	v_lshl_add_u64 v[46:47], v[42:43], 0, v[46:47]
	global_store_dwordx4 v[46:47], v[50:53], off
.LBB0_1780:
	s_or_b64 exec, exec, s[2:3]
	v_add_u32_e32 v46, 48, v44
	v_cmp_gt_i32_e32 vcc, s97, v46
	s_and_saveexec_b64 s[2:3], vcc
	s_cbranch_execz .LBB0_1782
	ds_read2_b32 v[232:233], v49 offset0:176 offset1:241
	ds_read2_b32 v[234:235], v48 offset0:50 offset1:115
	ds_read2_b32 v[236:237], v0 offset0:54 offset1:119
	ds_read2_b32 v[238:239], v48 offset0:180 offset1:245
	s_waitcnt lgkmcnt(0)
	v_bfe_u32 v240, v233, 16, 1
	v_add3_u32 v240, v233, v240, s60
	v_bfe_u32 v241, v232, 16, 1
	v_add3_u32 v241, v232, v241, s60
	v_lshrrev_b32_e32 v241, 16, v241
	v_and_or_b32 v50, v240, s33, v241
	v_bfe_u32 v240, v235, 16, 1
	v_add3_u32 v240, v235, v240, s60
	v_bfe_u32 v241, v234, 16, 1
	v_add3_u32 v241, v234, v241, s60
	v_lshrrev_b32_e32 v241, 16, v241
	v_and_or_b32 v51, v240, s33, v241
	v_bfe_u32 v240, v239, 16, 1
	v_add3_u32 v240, v239, v240, s60
	v_bfe_u32 v241, v238, 16, 1
	v_add3_u32 v241, v238, v241, s60
	v_lshrrev_b32_e32 v241, 16, v241
	v_and_or_b32 v52, v240, s33, v241
	v_bfe_u32 v240, v237, 16, 1
	v_add3_u32 v240, v237, v240, s60
	v_bfe_u32 v241, v236, 16, 1
	v_add3_u32 v241, v236, v241, s60
	v_lshrrev_b32_e32 v241, 16, v241
	v_and_or_b32 v53, v240, s33, v241
	v_ashrrev_i32_e32 v47, 31, v46
	v_lshlrev_b64 v[46:47], 12, v[46:47]
	v_lshl_add_u64 v[46:47], v[42:43], 0, v[46:47]
	global_store_dwordx4 v[46:47], v[50:53], off
.LBB0_1782:
	s_or_b64 exec, exec, s[2:3]
	v_add_u32_e32 v44, 56, v44
	v_cmp_gt_i32_e32 vcc, s97, v44
	s_and_saveexec_b64 s[2:3], vcc
	s_cbranch_execz .LBB0_1784
	ds_read2_b32 v[232:233], v49 offset0:184 offset1:249
	ds_read2_b32 v[234:235], v48 offset0:58 offset1:123
	ds_read2_b32 v[236:237], v48 offset0:188 offset1:253
	ds_read2_b32 v[238:239], v0 offset0:62 offset1:127
	s_waitcnt lgkmcnt(0)
	v_bfe_u32 v240, v233, 16, 1
	v_add3_u32 v240, v233, v240, s60
	v_bfe_u32 v241, v232, 16, 1
	v_add3_u32 v241, v232, v241, s60
	v_lshrrev_b32_e32 v241, 16, v241
	v_and_or_b32 v46, v240, s33, v241
	v_bfe_u32 v240, v235, 16, 1
	v_add3_u32 v240, v235, v240, s60
	v_bfe_u32 v241, v234, 16, 1
	v_add3_u32 v241, v234, v241, s60
	v_lshrrev_b32_e32 v241, 16, v241
	v_and_or_b32 v47, v240, s33, v241
	v_bfe_u32 v240, v237, 16, 1
	v_add3_u32 v240, v237, v240, s60
	v_bfe_u32 v241, v236, 16, 1
	v_add3_u32 v241, v236, v241, s60
	v_lshrrev_b32_e32 v241, 16, v241
	v_and_or_b32 v48, v240, s33, v241
	v_bfe_u32 v240, v239, 16, 1
	v_add3_u32 v240, v239, v240, s60
	v_bfe_u32 v241, v238, 16, 1
	v_add3_u32 v241, v238, v241, s60
	v_lshrrev_b32_e32 v241, 16, v241
	v_and_or_b32 v49, v240, s33, v241
	v_ashrrev_i32_e32 v45, 31, v44
	v_lshlrev_b64 v[44:45], 12, v[44:45]
	v_lshl_add_u64 v[42:43], v[42:43], 0, v[44:45]
	global_store_dwordx4 v[42:43], v[46:49], off
